# diff-attention tile loops: next-tile loads via scalar base + 32-bit vector offset (no 64-bit VALU adds); remaining packed bias FMA split into two FMAs with abs modifiers
# baseline (speedup 1.0000x reference)
; template <int DQK, int DV, bool BIAS> ...
;     ...
;     bf16x8 qf[NKS];
; #pragma unroll
;     for (int ks = 0; ks < NKS; ++ks) qf[ks] = ks < 4 ? *(const bf16x8*)(Qw + (size_t)r32 * ldq + ks * 16 + hi * 8) : *(const bf16x8*)(Q2w + (size_t)r32 * ldq2 + (ks - 4) * 16 + hi * 8);
; #pragma unroll
;     for (int ks = 0; ks < 4; ++ks) qf[ks] = scale_frag(qf[ks], cs);
; __device__ __forceinline__ void attn_phase(PPtr P, int li, LAS unsigned char* lds, int vcu, int wave, int lane) {
;     ...
;         const int b = vcu >> 6, h = (vcu >> 4) & 3, qb = vcu & 15;
;         const size_t seq0 = (size_t)b * SEQL, qrow = seq0 + qb * 256 + wave * 32;
;         const float slope = __builtin_amdgcn_exp2f(-2.f * (float)(h + 1));
;         f32x16 o1[4], o2[4];
;         attn_pass<64, 128, true>(lds, proj + qrow * LDP + C_AQ + h * 128, LDP, nullptr, 0, proj + seq0 * LDP + C_AK + h * 128, LDP, nullptr, 0, proj + seq0 * LDP + C_AV + h * 128, LDP, qb * 256 + wave * 32, 0.125f * LOG2E, slope * LOG2E, nullptr, o1);
.LBB0_573:
	s_cmp_lt_i32 s24, 5
	s_cselect_b64 s[4:5], -1, 0
	s_cmp_gt_i32 s25, 4
	s_cselect_b64 s[6:7], -1, 0
	s_and_b64 s[4:5], s[4:5], s[6:7]
	s_andn2_b64 vcc, exec, s[4:5]
	s_cbranch_vccnz .LBB0_751
	s_mov_b64 s[20:21], s[0:1]
	v_mov_b32_e32 v169, v1
	s_load_dwordx2 s[16:17], s[20:21], 0x118
	s_ashr_i32 s4, s33, 6
	v_readfirstlane_b32 s3, v169
	s_ashr_i32 s50, s3, 6
	s_ashr_i32 s5, s4, 31
	s_lshl_b32 s3, s33, 8
	s_lshl_b64 s[6:7], s[4:5], 12
	s_and_b32 s27, s3, 0xf00
	s_lshl_b32 s46, s50, 5
	s_bfe_u32 s8, s33, 0x20004
	s_or_b32 s3, s6, s27
	s_ashr_i32 s47, s46, 31
	s_add_u32 s5, s3, s46
	s_addc_u32 s6, s7, s47
	s_not_b32 s3, s8
	s_mulk_i32 s6, 0x1940
	s_mul_hi_u32 s7, s5, 0x1940
	s_lshl_b32 s3, s3, 1
	s_add_i32 s7, s7, s6
	s_mulk_i32 s5, 0x1940
	s_waitcnt lgkmcnt(0)
	s_add_u32 s5, s16, s5
	v_mov_b32_e32 v32, v1
	s_addc_u32 s6, s17, s7
	s_lshl_b32 s9, s8, 8
	s_add_u32 s18, s5, s9
	v_and_b32_e32 v33, 31, v32
	v_mul_u32_u24_e32 v2, 0xca0, v33
	s_addc_u32 s19, s6, 0
	v_bfe_u32 v34, v32, 5, 1
	v_lshlrev_b32_e32 v150, 1, v2
	v_mov_b32_e32 v151, 0
	v_lshl_add_u64 v[2:3], s[18:19], 0, v[150:151]
	v_lshlrev_b32_e32 v150, 4, v34
	v_lshl_add_u64 v[18:19], v[2:3], 0, v[150:151]
	global_load_dwordx4 v[2:5], v[18:19], off
	global_load_dwordx4 v[6:9], v[18:19], off offset:32
	global_load_dwordx4 v[10:13], v[18:19], off offset:64
	global_load_dwordx4 v[14:17], v[18:19], off offset:96
	s_movk_i32 s7, 0x1940
	s_mov_b32 s6, 0x3e38aa3b
	s_mul_i32 s49, s4, 0x1940000
	s_mul_hi_i32 s48, s4, 0x1940000
	s_add_u32 s4, s16, s49
	s_addc_u32 s5, s17, s48
	s_add_u32 s4, s4, s9
	s_addc_u32 s5, s5, 0
	s_mov_b32 s8, 0x65000
	v_lshlrev_b32_e32 v173, 2, v34
	s_mov_b32 s22, 0xc1000000
	s_mov_b32 s34, 0xc1200000
	s_mov_b32 s36, 0xc1800000
	s_mov_b32 s38, 0xc1900000
	s_mov_b32 s40, 0xc1c00000
	s_mov_b32 s42, 0xc1d00000
	s_mov_b32 s51, 0
	s_mov_b32 s23, 0xc1100000
	s_mov_b32 s35, 0xc1300000
	s_mov_b32 s37, 0xc1880000
	s_mov_b32 s39, 0xc1980000
	s_mov_b32 s41, 0xc1c80000
	s_mov_b32 s43, 0xc1d80000
	s_mov_b32 s52, 0x41000000
	v_mov_b32_e32 v176, v151
	v_mov_b32_e32 v66, v151
	v_mov_b32_e32 v67, v151
	v_mov_b32_e32 v68, v151
	v_mov_b32_e32 v69, v151
	v_mov_b32_e32 v70, v151
	v_mov_b32_e32 v71, v151
	v_mov_b32_e32 v72, v151
	v_mov_b32_e32 v73, v151
	v_mov_b32_e32 v74, v151
	v_mov_b32_e32 v75, v151
	v_mov_b32_e32 v76, v151
	v_mov_b32_e32 v77, v151
	v_mov_b32_e32 v78, v151
	v_mov_b32_e32 v79, v151
	v_mov_b32_e32 v80, v151
	v_mov_b32_e32 v81, v151
	s_waitcnt vmcnt(0)
; __device__ __forceinline__ unsigned cvtpk(float lo, float hi) { typedef __bf16 bf2 __attribute__((ext_vector_type(2))); f32x2 v = {lo, hi}; bf2 b = __builtin_convertvector(v, bf2); return __builtin_bit_cast(unsigned, b); }
; template <int DQK, int DV, bool BIAS> ...
;     ...
;     for (int ks = 0; ks < NKS; ++ks) qf[ks] = ks < 4 ? *(const bf16x8*)(Qw + (size_t)r32 * ldq + ks * 16 + hi * 8) : *(const bf16x8*)(Q2w + (size_t)r32 * ldq2 + (ks - 4) * 16 + hi * 8);
; #pragma unroll
;     for (int ks = 0; ks < 4; ++ks) qf[ks] = scale_frag(qf[ks], cs);
;     if constexpr (DQK == 96) {
;         const float* rp = ropetab + ((size_t)(qpos0 + r32) * 16) * 2;
; #pragma unroll
;         for (int ks = 4; ks < 6; ++ks) {
;             const f32x4 c0 = *(const f32x4*)(rp + ((ks - 4) * 8 + hi * 4) * 2), c1 = *(const f32x4*)(rp + ((ks - 4) * 8 + hi * 4 + 2) * 2);
;             const u32x4 w = __builtin_bit_cast(u32x4, qf[ks]); u32x4 ow;
;             { const float a = bflo(w.x) * cs, b = bfhi(w.x) * cs; ow.x = cvtpk(a * c0[0] - b * c0[1], a * c0[1] + b * c0[0]); }
;             { const float a = bflo(w.y) * cs, b = bfhi(w.y) * cs; ow.y = cvtpk(a * c0[2] - b * c0[3], a * c0[3] + b * c0[2]); }
;             { const float a = bflo(w.z) * cs, b = bfhi(w.z) * cs; ow.z = cvtpk(a * c1[0] - b * c1[1], a * c1[1] + b * c1[0]); }
;             { const float a = bflo(w.w) * cs, b = bfhi(w.w) * cs; ow.w = cvtpk(a * c1[2] - b * c1[3], a * c1[3] + b * c1[2]); }
;             qf[ks] = __builtin_bit_cast(bf16x8, ow);
;         }
;     }
; #pragma unroll
;     for (int d = 0; d < NDT; ++d)
; #pragma unroll
;         for (int r = 0; r < 16; ++r) o[d][r] = 0.f;
; #pragma unroll
;     for (int ks = 0; ks < NKS; ++ks) asm volatile("" : "+v"(qf[ks]));
;     float mhat = 0.f, l = 0.f; f32x16 negm;
; #pragma unroll
;     for (int r = 0; r < 16; ++r) negm[r] = 0.f;
;     constexpr int TPB = (DV == 64) ? 2 : 1, NG = SEQL / 64 / TPB;
;     u32x4 kreg[TPB], k2reg[TPB], vreg[TPB][NVL];
;     const bf16_t* kptr = Kg + (size_t)(tid >> 3) * ldk + (tid & 7) * 8;
;     const bf16_t* k2ptr = (DQK == 96) ? K2g + (size_t)(tid >> 2) * ldk2 + (tid & 3) * 8 : nullptr;
;     ...
;     u32x4 pw[4];
; #pragma unroll
;     for (int j = 0; j < TPB; ++j) { ATT_LOAD(j, j); ATT_STORE(j, j); }
; #pragma unroll
;     for (int j = 0; j < TPB; ++j) ATT_LOAD(TPB + j, j);
;     const float qp = (float)(qpos0 + r32);
	v_lshlrev_b32_e32 v18, 16, v2
	v_and_b32_e32 v19, 0xffff0000, v2
	v_lshlrev_b32_e32 v2, 16, v3
	v_and_b32_e32 v3, 0xffff0000, v3
	v_lshlrev_b32_e32 v30, 16, v14
	v_pk_mul_f32 v[2:3], v[2:3], s[6:7] op_sel_hi:[1,0]
	v_and_b32_e32 v31, 0xffff0000, v14
	v_cvt_pk_bf16_f32 v115, v2, v3
	v_pk_mul_f32 v[2:3], v[30:31], s[6:7] op_sel_hi:[1,0]
	v_lshlrev_b32_e32 v22, 16, v6
	v_cvt_pk_bf16_f32 v126, v2, v3
	v_lshlrev_b32_e32 v2, 16, v15
	v_and_b32_e32 v3, 0xffff0000, v15
	v_pk_mul_f32 v[2:3], v[2:3], s[6:7] op_sel_hi:[1,0]
	v_and_b32_e32 v23, 0xffff0000, v6
	v_cvt_pk_bf16_f32 v127, v2, v3
	v_lshlrev_b32_e32 v2, 16, v16
	v_and_b32_e32 v3, 0xffff0000, v16
	v_pk_mul_f32 v[2:3], v[2:3], s[6:7] op_sel_hi:[1,0]
	v_lshlrev_b32_e32 v24, 16, v8
	v_cvt_pk_bf16_f32 v128, v2, v3
	v_lshlrev_b32_e32 v2, 16, v17
	v_and_b32_e32 v3, 0xffff0000, v17
	v_and_b32_e32 v25, 0xffff0000, v8
	v_pk_mul_f32 v[22:23], v[22:23], s[6:7] op_sel_hi:[1,0]
	v_pk_mul_f32 v[2:3], v[2:3], s[6:7] op_sel_hi:[1,0]
	v_lshlrev_b32_e32 v20, 16, v4
	v_and_b32_e32 v21, 0xffff0000, v4
	v_lshlrev_b32_e32 v4, 16, v5
	v_and_b32_e32 v5, 0xffff0000, v5
	v_pk_mul_f32 v[24:25], v[24:25], s[6:7] op_sel_hi:[1,0]
	v_cvt_pk_bf16_f32 v118, v22, v23
	v_cvt_pk_bf16_f32 v129, v2, v3
	v_ashrrev_i32_e32 v22, 3, v32
	v_mov_b64_e32 v[2:3], s[4:5]
	v_lshlrev_b32_e32 v23, 4, v32
	v_pk_mul_f32 v[4:5], v[4:5], s[6:7] op_sel_hi:[1,0]
	v_cvt_pk_bf16_f32 v120, v24, v25
	v_mad_i64_i32 v[2:3], s[10:11], v22, s7, v[2:3]
	v_and_b32_e32 v14, 0x70, v23
	v_mov_b32_e32 v15, v151
	v_bfe_u32 v24, v32, 2, 6
	v_cvt_pk_bf16_f32 v117, v4, v5
	v_lshl_add_u64 v[144:145], v[2:3], 0, v[14:15]
	v_subrev_u32_e32 v232, s4, v144
	s_sub_u32 s98, s4, s16
	s_subb_u32 s99, s5, s17
	v_mul_u32_u24_e32 v2, 0xca0, v24
	v_lshlrev_b32_e32 v4, 3, v32
	v_lshlrev_b32_e32 v2, 1, v2
	v_mov_b32_e32 v3, v151
	v_and_b32_e32 v25, 24, v4
	v_lshl_add_u64 v[2:3], s[4:5], 0, v[2:3]
	v_lshlrev_b32_e32 v4, 1, v25
	v_mov_b32_e32 v5, v151
	v_lshl_add_u64 v[16:17], v[2:3], 0, v[4:5]
	v_and_b32_e32 v2, 0xffffffe0, v22
	v_lshlrev_b32_e32 v6, 16, v7
	v_and_b32_e32 v7, 0xffff0000, v7
	v_lshlrev_b32_e32 v8, 16, v9
	v_and_b32_e32 v9, 0xffff0000, v9
	v_lshlrev_b32_e32 v26, 16, v10
	v_and_b32_e32 v27, 0xffff0000, v10
	v_lshlrev_b32_e32 v10, 16, v11
	v_and_b32_e32 v11, 0xffff0000, v11
	v_lshlrev_b32_e32 v28, 16, v12
	v_and_b32_e32 v29, 0xffff0000, v12
	v_lshlrev_b32_e32 v12, 16, v13
	v_and_b32_e32 v13, 0xffff0000, v13
	v_pk_mul_f32 v[18:19], v[18:19], s[6:7] op_sel_hi:[1,0]
	v_ashrrev_i32_e32 v3, 31, v2
	v_pk_mul_f32 v[20:21], v[20:21], s[6:7] op_sel_hi:[1,0]
	v_pk_mul_f32 v[6:7], v[6:7], s[6:7] op_sel_hi:[1,0]
	v_pk_mul_f32 v[8:9], v[8:9], s[6:7] op_sel_hi:[1,0]
	v_pk_mul_f32 v[26:27], v[26:27], s[6:7] op_sel_hi:[1,0]
	v_pk_mul_f32 v[10:11], v[10:11], s[6:7] op_sel_hi:[1,0]
	v_pk_mul_f32 v[28:29], v[28:29], s[6:7] op_sel_hi:[1,0]
	v_pk_mul_f32 v[12:13], v[12:13], s[6:7] op_sel_hi:[1,0]
	v_cvt_pk_bf16_f32 v114, v18, v19
	v_lshlrev_b64 v[18:19], 1, v[2:3]
	v_cvt_pk_bf16_f32 v116, v20, v21
	v_cvt_pk_bf16_f32 v119, v6, v7
	v_cvt_pk_bf16_f32 v121, v8, v9
	v_cvt_pk_bf16_f32 v122, v26, v27
	v_cvt_pk_bf16_f32 v123, v10, v11
	v_cvt_pk_bf16_f32 v124, v28, v29
	v_cvt_pk_bf16_f32 v125, v12, v13
	v_lshl_add_u64 v[10:11], v[16:17], 0, v[18:19]
	global_load_dwordx4 v[2:5], v[144:145], off offset:1024
	global_load_dwordx4 v[6:9], v[10:11], off offset:2048
	v_add_u32_e32 v10, 0x200, v32
	v_ashrrev_i32_e32 v10, 3, v10
	v_and_b32_e32 v10, 0xffffffe0, v10
	v_ashrrev_i32_e32 v11, 31, v10
	v_lshlrev_b64 v[20:21], 1, v[10:11]
	v_lshl_add_u64 v[10:11], v[16:17], 0, v[20:21]
	global_load_dwordx4 v[10:13], v[10:11], off offset:2048
	s_movk_i32 s6, 0x90
	v_mul_lo_u32 v15, v22, s6
	s_mov_b64 s[10:11], 0x65800
	v_and_b32_e32 v22, 0xfc0, v23
	v_and_b32_e32 v27, 48, v23
	v_add_u32_e32 v15, 0, v15
	v_and_b32_e32 v23, 0xfffff000, v23
	v_add3_u32 v22, 0, v22, v27
	v_add_u32_e32 v168, v15, v14
	v_lshl_add_u64 v[14:15], v[16:17], 0, s[10:11]
	v_add_u32_e32 v171, v22, v23
	v_lshl_add_u64 v[16:17], v[14:15], 0, v[18:19]
	v_add_co_u32_e32 v22, vcc, s8, v144
	v_lshl_add_u64 v[14:15], v[14:15], 0, v[20:21]
	s_nop 0
	v_addc_co_u32_e32 v23, vcc, 0, v145, vcc
	global_load_dwordx4 v[130:133], v[16:17], off
	global_load_dwordx4 v[134:137], v[14:15], off
	global_load_dwordx4 v[138:141], v[22:23], off offset:1024
	v_cvt_f32_i32_e32 v28, s3
	s_add_i32 s3, s46, s27
	v_lshrrev_b32_e32 v26, 2, v32
	s_waitcnt vmcnt(5)
	ds_write_b128 v168, v[2:5]
	s_waitcnt vmcnt(4)
	ds_write_b128 v171, v[6:9] offset:18432
	s_waitcnt vmcnt(3)
	ds_write_b128 v171, v[10:13] offset:26624
	v_or_b32_e32 v2, s3, v33
	v_cvt_f32_i32_e32 v172, v2
	v_and_or_b32 v2, v26, 3, v173
	v_lshlrev_b32_e32 v3, 1, v32
	v_mad_u32_u24 v22, v33, s6, 0
	v_lshl_add_u32 v2, v2, 6, 0
	v_and_b32_e32 v3, 32, v3
	s_or_b32 s6, s49, s9
	v_exp_f32_e32 v27, v28
	v_add3_u32 v174, v2, v3, v25
	v_mov_b32_e32 v2, s6
	v_mov_b32_e32 v3, s48
	v_mad_u64_u32 v[2:3], s[6:7], v24, s7, v[2:3]
	v_and_b32_e32 v4, 3, v32
	v_lshl_or_b32 v2, v4, 4, v2
	v_lshl_add_u64 v[4:5], v[2:3], 0, v[20:21]
	v_lshl_add_u64 v[2:3], v[2:3], 0, v[18:19]
	v_mov_b32_e32 v16, v151
	v_mov_b32_e32 v17, v151
	v_mbcnt_lo_u32_b32 v18, -1, 0
	v_mul_f32_e32 v142, 0x3fb8aa3b, v27
	v_mov_b32_e32 v231, v4
	v_lshl_add_u64 v[146:147], s[16:17], 0, v[4:5]
	v_mov_b32_e32 v230, v2
	v_lshl_add_u64 v[148:149], s[16:17], 0, v[2:3]
	v_mov_b32_e32 v2, v151
	v_mov_b32_e32 v3, v151
	v_mov_b32_e32 v4, v151
	v_mov_b32_e32 v5, v151
	v_mov_b32_e32 v6, v151
	v_mov_b32_e32 v7, v151
	v_mov_b32_e32 v8, v151
	v_mov_b32_e32 v9, v151
	v_mov_b32_e32 v10, v151
	v_mov_b32_e32 v11, v151
	v_mov_b32_e32 v12, v151
	v_mov_b32_e32 v13, v151
	v_mov_b32_e32 v14, v151
	v_mov_b32_e32 v15, v151
	s_mov_b32 s10, -2.0
	v_add_u32_e32 v175, v22, v150
	v_mbcnt_hi_u32_b32 v170, -1, v18
	v_mov_b64_e32 v[32:33], v[16:17]
	v_mov_b64_e32 v[48:49], v[16:17]
	v_mov_b64_e32 v[64:65], v[16:17]
	v_mov_b32_e32 v143, v142
	s_mov_b64 s[6:7], 0
	s_mov_b32 s8, 0xc2000000
	s_mov_b32 s11, 0xc0400000
	v_mov_b64_e32 v[30:31], v[14:15]
	v_mov_b64_e32 v[28:29], v[12:13]
	v_mov_b64_e32 v[26:27], v[10:11]
	v_mov_b64_e32 v[24:25], v[8:9]
	v_mov_b64_e32 v[22:23], v[6:7]
	v_mov_b64_e32 v[20:21], v[4:5]
	v_mov_b64_e32 v[18:19], v[2:3]
	v_mov_b64_e32 v[46:47], v[14:15]
	v_mov_b64_e32 v[44:45], v[12:13]
	v_mov_b64_e32 v[42:43], v[10:11]
	v_mov_b64_e32 v[40:41], v[8:9]
	v_mov_b64_e32 v[38:39], v[6:7]
	v_mov_b64_e32 v[36:37], v[4:5]
	v_mov_b64_e32 v[34:35], v[2:3]
	v_mov_b64_e32 v[62:63], v[14:15]
	v_mov_b64_e32 v[60:61], v[12:13]
	v_mov_b64_e32 v[58:59], v[10:11]
	v_mov_b64_e32 v[56:57], v[8:9]
	v_mov_b64_e32 v[54:55], v[6:7]
	v_mov_b64_e32 v[52:53], v[4:5]
	v_mov_b64_e32 v[50:51], v[2:3]
	s_branch .LBB0_576

; #define LAS __attribute__((address_space(3)))
; __device__ __forceinline__ float max3f(float a, float b, float c) { float r; asm("v_max3_f32 %0, %1, %2, %3" : "=v"(r) : "v"(a), "v"(b), "v"(c)); return r; }
; template <int DQK, int DV, bool BIAS> ...
;     ...
;     for (int g = 0; g < NG; ++g) {
;         const int pair = g & 1;
;         __syncthreads();
;         if (g + 1 < NG) {
; #pragma unroll
;             for (int j = 0; j < TPB; ++j) ATT_STORE((pair ^ 1) * TPB + j, j);
;             if (g + 2 < NG) {
; #pragma unroll
;                 for (int j = 0; j < TPB; ++j) ATT_LOAD((g + 2) * TPB + j, j);
;             }
;         }
; #pragma unroll
;       for (int sub = 0; sub < TPB; ++sub) {
;         const int t = g * TPB + sub, buf = pair * TPB + sub, vcur = buf;
;         f32x16 p0, p1;
;         const LAS unsigned char* kb = lds + buf * KBUF + r32 * KP + hi * 16;
; #pragma unroll
;         for (int ks = 0; ks < NKS; ++ks) {
;             const bf16x8 k0 = *(const LAS bf16x8*)(kb + ks * 32), k1 = *(const LAS bf16x8*)(kb + 32 * KP + ks * 32);
;             if (ks == 0) { p0 = __builtin_amdgcn_mfma_f32_32x32x16_bf16(k0, qf[0], negm, 0, 0, 0); p1 = __builtin_amdgcn_mfma_f32_32x32x16_bf16(k1, qf[0], negm, 0, 0, 0); }
;             else { p0 = __builtin_amdgcn_mfma_f32_32x32x16_bf16(k0, qf[ks], p0, 0, 0, 0); p1 = __builtin_amdgcn_mfma_f32_32x32x16_bf16(k1, qf[ks], p1, 0, 0, 0); }
;         }
;         if (BIAS) {
;             asm volatile("s_nop 15\n\ts_nop 7" : "+v"(p0), "+v"(p1));
;             const float d0 = qp - (float)(t * 64 + 4 * hi);
; #pragma unroll
;             for (int r = 0; r < 16; ++r) { const float dk = d0 - (float)((r & 3) + 8 * (r >> 2)); p0[r] = p0[r] - sl2 * fabsf(dk); p1[r] = p1[r] - sl2 * fabsf(dk - 32.f); }
;         } else {
;             asm volatile("s_nop 15\n\ts_nop 7" : "+v"(p0), "+v"(p1));
;         }
;         float mxa = max3f(p0[0], p0[1], p1[0]), mxb = max3f(p0[2], p0[3], p1[1]); mxa = max3f(mxa, p1[2], p1[3]);
; #pragma unroll
;         for (int r = 4; r < 16; r += 4) { mxa = max3f(mxa, p0[r], p0[r + 1]); mxb = max3f(mxb, p0[r + 2], p0[r + 3]); mxa = max3f(mxa, p1[r], p1[r + 1]); mxb = max3f(mxb, p1[r + 2], p1[r + 3]); }
;         float mx = fmaxf(mxa, mxb);
;         if (__any(mx > 8.f)) {
.LBB0_576:
	s_cmp_lt_u32 s51, 62
	s_cselect_b64 s[44:45], -1, 0
	s_cmp_gt_u32 s51, 61
	s_waitcnt lgkmcnt(0)
	s_barrier
	s_waitcnt vmcnt(0)
	ds_write_b128 v168, v[138:141] offset:9216
	ds_write_b128 v171, v[130:133] offset:34816
	ds_write_b128 v171, v[134:137] offset:43008
	s_cbranch_scc1 .LBB0_578
	s_add_u32 s100, s6, 0xca000
	s_addc_u32 s101, s7, 0
	s_add_u32 s100, s100, s16
	s_addc_u32 s101, s101, s17
	global_load_dwordx4 v[130:133], v230, s[100:101] offset:2048
	global_load_dwordx4 v[134:137], v231, s[100:101] offset:2048
	s_add_u32 s100, s100, s98
	s_addc_u32 s101, s101, s99
	global_load_dwordx4 v[138:141], v232, s[100:101] offset:1024
.LBB0_578:
	ds_read_b128 v[82:85], v175
	ds_read_b128 v[152:155], v175 offset:32
	ds_read_b128 v[156:159], v175 offset:4608
	ds_read_b128 v[160:163], v175 offset:4640
	v_cvt_f32_u32_e32 v150, v173
	s_waitcnt lgkmcnt(3)
	v_mfma_f32_32x32x16_bf16 v[98:113], v[82:85], v[114:117], v[66:81]
	v_sub_f32_e32 v178, v172, v150
	v_add_f32_e32 v179, -1.0, v178
	s_waitcnt lgkmcnt(1)
	v_mfma_f32_32x32x16_bf16 v[82:97], v[156:159], v[114:117], v[66:81]
	v_mfma_f32_32x32x16_bf16 v[98:113], v[152:155], v[118:121], v[98:113]
	ds_read_b128 v[152:155], v175 offset:64
	ds_read_b128 v[156:159], v175 offset:96
	s_waitcnt lgkmcnt(2)
	v_mfma_f32_32x32x16_bf16 v[82:97], v[160:163], v[118:121], v[82:97]
	s_waitcnt lgkmcnt(1)
	v_mfma_f32_32x32x16_bf16 v[98:113], v[152:155], v[122:125], v[98:113]
	ds_read_b128 v[152:155], v175 offset:4672
	ds_read_b128 v[160:163], v175 offset:4704
	s_waitcnt lgkmcnt(1)
	v_mfma_f32_32x32x16_bf16 v[82:97], v[152:155], v[122:125], v[82:97]
	v_mfma_f32_32x32x16_bf16 v[98:113], v[156:159], v[126:129], v[98:113]
	s_waitcnt lgkmcnt(0)
	v_mfma_f32_32x32x16_bf16 v[82:97], v[160:163], v[126:129], v[82:97]
	s_nop 15
	s_nop 7
	s_nop 9
	v_fma_f32 v156, -v142, |v178|, v98
	v_fma_f32 v157, -v143, |v179|, v99
	v_pk_add_f32 v[98:99], v[178:179], s[8:9] op_sel_hi:[1,0]
	s_nop 0
	v_fma_f32 v99, -v143, |v99|, v83
	v_fma_f32 v98, -v142, |v98|, v82
	v_pk_add_f32 v[82:83], v[178:179], s[10:11] op_sel_hi:[0,1]
	v_fma_f32 v161, -v143, |v83|, v101
	v_fma_f32 v160, -v142, |v82|, v100
	v_pk_add_f32 v[82:83], v[82:83], s[8:9] op_sel_hi:[1,0]
	v_fma_f32 v153, -v143, |v83|, v85
	v_fma_f32 v152, -v142, |v82|, v84
	v_pk_add_f32 v[82:83], v[178:179], s[22:23] op_sel_hi:[0,1]
	v_fma_f32 v165, -v143, |v83|, v103
	v_fma_f32 v164, -v142, |v82|, v102
	v_pk_add_f32 v[82:83], v[82:83], s[8:9] op_sel_hi:[1,0]
	v_fma_f32 v103, -v143, |v83|, v87
	v_fma_f32 v102, -v142, |v82|, v86
	v_pk_add_f32 v[82:83], v[178:179], s[34:35] op_sel_hi:[0,1]
	v_fma_f32 v167, -v143, |v83|, v105
	v_fma_f32 v166, -v142, |v82|, v104
	v_pk_add_f32 v[82:83], v[82:83], s[8:9] op_sel_hi:[1,0]
	v_fma_f32 v155, -v143, |v83|, v89
	v_fma_f32 v154, -v142, |v82|, v88
	v_pk_add_f32 v[82:83], v[178:179], s[36:37] op_sel_hi:[0,1]
	v_fma_f32 v159, -v143, |v83|, v107
	v_fma_f32 v158, -v142, |v82|, v106
	v_pk_add_f32 v[82:83], v[82:83], s[8:9] op_sel_hi:[1,0]
	v_fma_f32 v101, -v143, |v83|, v91
	v_fma_f32 v100, -v142, |v82|, v90
	v_pk_add_f32 v[82:83], v[178:179], s[38:39] op_sel_hi:[0,1]
	v_fma_f32 v163, -v143, |v83|, v109
	v_fma_f32 v162, -v142, |v82|, v108
	v_pk_add_f32 v[82:83], v[82:83], s[8:9] op_sel_hi:[1,0]
	v_fma_f32 v105, -v143, |v83|, v93
	v_fma_f32 v104, -v142, |v82|, v92
	v_pk_add_f32 v[82:83], v[178:179], s[40:41] op_sel_hi:[0,1]
	v_fma_f32 v111, -v143, |v83|, v111
	v_fma_f32 v110, -v142, |v82|, v110
	v_pk_add_f32 v[82:83], v[82:83], s[8:9] op_sel_hi:[1,0]
	v_fma_f32 v107, -v143, |v83|, v95
	v_fma_f32 v106, -v142, |v82|, v94
	v_pk_add_f32 v[82:83], v[178:179], s[42:43] op_sel_hi:[0,1]
	v_fma_f32 v113, -v143, |v83|, v113
	v_fma_f32 v112, -v142, |v82|, v112
	v_pk_add_f32 v[82:83], v[82:83], s[8:9] op_sel_hi:[1,0]
	v_fma_f32 v109, -v143, |v83|, v97
	v_fma_f32 v108, -v142, |v82|, v96
	v_max3_f32 v82, v156, v157, v98
	v_max3_f32 v83, v160, v161, v99
	v_max3_f32 v82, v82, v152, v153
	v_max3_f32 v83, v83, v166, v167
	v_max3_f32 v82, v82, v164, v165
	v_max3_f32 v83, v83, v154, v155
	v_max3_f32 v82, v82, v102, v103
	v_max3_f32 v83, v83, v162, v163
	v_max3_f32 v82, v82, v158, v159
	v_max3_f32 v83, v83, v104, v105
	v_max3_f32 v82, v82, v100, v101
	v_max3_f32 v83, v83, v112, v113
	v_max3_f32 v82, v82, v110, v111
	v_max3_f32 v83, v83, v108, v109
	v_max3_f32 v82, v82, v106, v107
	v_max_f32_e32 v82, v82, v83
	v_cmp_gt_f32_e32 vcc, 0xc3400000, v82
	s_cmp_eq_u64 vcc, exec
	s_cbranch_scc1 .Lsk1_p4a1
; template <int DQK, int DV, bool BIAS> ...
;     ...
;         if (__any(mx > 8.f)) {
;             mx = fmaxf(mx, __shfl_xor(mx, 32));
;             const float dl = fmaxf(mx, 0.f); mhat += dl;
;             const float f = __builtin_amdgcn_exp2f(-dl);
; #pragma unroll
;             for (int r = 0; r < 16; ++r) { p0[r] -= dl; p1[r] -= dl; negm[r] = -mhat; }
;             l *= f;
; #pragma unroll
;             for (int d = 0; d < NDT; ++d)
; #pragma unroll
;                 for (int r = 0; r < 16; ++r) o[d][r] *= f;
;         }
	v_cmp_lt_f32_e32 vcc, s52, v82
	s_cbranch_vccz .LBB0_580
	v_and_b32_e32 v67, 64, v170
	v_xor_b32_e32 v66, 32, v170
	v_add_u32_e32 v67, 64, v67
	v_cmp_lt_i32_e32 vcc, v66, v67
	s_nop 1
	v_cndmask_b32_e32 v66, v170, v66, vcc
	v_lshlrev_b32_e32 v66, 2, v66
	ds_bpermute_b32 v66, v66, v82
	s_waitcnt lgkmcnt(0)
	v_max3_f32 v67, v82, v66, 0
	v_exp_f32_e64 v66, -v67
	v_add_f32_e32 v176, v176, v67
	v_xor_b32_e32 v82, 0x80000000, v176
	v_sub_f32_e32 v98, v98, v67
	v_sub_f32_e32 v99, v99, v67
	v_sub_f32_e32 v152, v152, v67
	v_sub_f32_e32 v153, v153, v67
	v_sub_f32_e32 v102, v102, v67
	v_sub_f32_e32 v103, v103, v67
	v_sub_f32_e32 v154, v154, v67
	v_sub_f32_e32 v155, v155, v67
	v_sub_f32_e32 v100, v100, v67
	v_sub_f32_e32 v101, v101, v67
	v_sub_f32_e32 v104, v104, v67
	v_sub_f32_e32 v105, v105, v67
	v_sub_f32_e32 v106, v106, v67
	v_sub_f32_e32 v107, v107, v67
	v_sub_f32_e32 v108, v108, v67
	v_sub_f32_e32 v109, v109, v67
	v_pk_mul_f32 v[64:65], v[64:65], v[66:67] op_sel_hi:[1,0]
	v_pk_mul_f32 v[62:63], v[62:63], v[66:67] op_sel_hi:[1,0]
	v_pk_mul_f32 v[60:61], v[60:61], v[66:67] op_sel_hi:[1,0]
	v_pk_mul_f32 v[58:59], v[58:59], v[66:67] op_sel_hi:[1,0]
	v_pk_mul_f32 v[56:57], v[56:57], v[66:67] op_sel_hi:[1,0]
	v_pk_mul_f32 v[54:55], v[54:55], v[66:67] op_sel_hi:[1,0]
	v_pk_mul_f32 v[52:53], v[52:53], v[66:67] op_sel_hi:[1,0]
	v_pk_mul_f32 v[50:51], v[50:51], v[66:67] op_sel_hi:[1,0]
	v_pk_mul_f32 v[48:49], v[48:49], v[66:67] op_sel_hi:[1,0]
	v_pk_mul_f32 v[46:47], v[46:47], v[66:67] op_sel_hi:[1,0]
	v_pk_mul_f32 v[44:45], v[44:45], v[66:67] op_sel_hi:[1,0]
	v_pk_mul_f32 v[42:43], v[42:43], v[66:67] op_sel_hi:[1,0]
	v_pk_mul_f32 v[40:41], v[40:41], v[66:67] op_sel_hi:[1,0]
	v_pk_mul_f32 v[38:39], v[38:39], v[66:67] op_sel_hi:[1,0]
	v_pk_mul_f32 v[36:37], v[36:37], v[66:67] op_sel_hi:[1,0]
	v_pk_mul_f32 v[34:35], v[34:35], v[66:67] op_sel_hi:[1,0]
	v_pk_mul_f32 v[32:33], v[32:33], v[66:67] op_sel_hi:[1,0]
	v_pk_mul_f32 v[30:31], v[30:31], v[66:67] op_sel_hi:[1,0]
	v_pk_mul_f32 v[28:29], v[28:29], v[66:67] op_sel_hi:[1,0]
	v_pk_mul_f32 v[26:27], v[26:27], v[66:67] op_sel_hi:[1,0]
	v_pk_mul_f32 v[24:25], v[24:25], v[66:67] op_sel_hi:[1,0]
	v_pk_mul_f32 v[22:23], v[22:23], v[66:67] op_sel_hi:[1,0]
	v_pk_mul_f32 v[20:21], v[20:21], v[66:67] op_sel_hi:[1,0]
	v_pk_mul_f32 v[18:19], v[18:19], v[66:67] op_sel_hi:[1,0]
	v_pk_mul_f32 v[16:17], v[16:17], v[66:67] op_sel_hi:[1,0]
	v_pk_mul_f32 v[14:15], v[14:15], v[66:67] op_sel_hi:[1,0]
	v_pk_mul_f32 v[12:13], v[12:13], v[66:67] op_sel_hi:[1,0]
	v_pk_mul_f32 v[10:11], v[10:11], v[66:67] op_sel_hi:[1,0]
	v_pk_mul_f32 v[8:9], v[8:9], v[66:67] op_sel_hi:[1,0]
	v_pk_mul_f32 v[6:7], v[6:7], v[66:67] op_sel_hi:[1,0]
	v_pk_mul_f32 v[4:5], v[4:5], v[66:67] op_sel_hi:[1,0]
	v_pk_mul_f32 v[2:3], v[2:3], v[66:67] op_sel_hi:[1,0]
	v_sub_f32_e32 v156, v156, v67
	v_sub_f32_e32 v157, v157, v67
	v_sub_f32_e32 v160, v160, v67
	v_sub_f32_e32 v161, v161, v67
	v_sub_f32_e32 v164, v164, v67
	v_sub_f32_e32 v165, v165, v67
	v_sub_f32_e32 v166, v166, v67
	v_sub_f32_e32 v167, v167, v67
	v_sub_f32_e32 v158, v158, v67
	v_sub_f32_e32 v159, v159, v67
	v_sub_f32_e32 v162, v162, v67
	v_sub_f32_e32 v163, v163, v67
	v_sub_f32_e32 v110, v110, v67
	v_sub_f32_e32 v111, v111, v67
	v_sub_f32_e32 v112, v112, v67
	v_sub_f32_e32 v113, v113, v67
	v_mul_f32_e32 v151, v151, v66
	v_mov_b32_e32 v66, v82
	v_mov_b32_e32 v67, v82
	v_mov_b32_e32 v68, v82
	v_mov_b32_e32 v69, v82
	v_mov_b32_e32 v70, v82
	v_mov_b32_e32 v71, v82
	v_mov_b32_e32 v72, v82
	v_mov_b32_e32 v73, v82
	v_mov_b32_e32 v74, v82
	v_mov_b32_e32 v75, v82
	v_mov_b32_e32 v76, v82
	v_mov_b32_e32 v77, v82
	v_mov_b32_e32 v78, v82
	v_mov_b32_e32 v79, v82
	v_mov_b32_e32 v80, v82
	v_mov_b32_e32 v81, v82
	s_branch .LBB0_581

; #define LAS __attribute__((address_space(3)))
; template <int DQK, int DV, bool BIAS> ...
;     ...
;     for (int g = 0; g < NG; ++g) {
;         const int pair = g & 1;
;         __syncthreads();
;         if (g + 1 < NG) {
; #pragma unroll
;             for (int j = 0; j < TPB; ++j) ATT_STORE((pair ^ 1) * TPB + j, j);
;             if (g + 2 < NG) {
; #pragma unroll
;                 for (int j = 0; j < TPB; ++j) ATT_LOAD((g + 2) * TPB + j, j);
;             }
;         }
; #pragma unroll
;       for (int sub = 0; sub < TPB; ++sub) {
;         const int t = g * TPB + sub, buf = pair * TPB + sub, vcur = buf;
;         f32x16 p0, p1;
;         const LAS unsigned char* kb = lds + buf * KBUF + r32 * KP + hi * 16;
; #pragma unroll
;         for (int ks = 0; ks < NKS; ++ks) {
;             const bf16x8 k0 = *(const LAS bf16x8*)(kb + ks * 32), k1 = *(const LAS bf16x8*)(kb + 32 * KP + ks * 32);
;             if (ks == 0) { p0 = __builtin_amdgcn_mfma_f32_32x32x16_bf16(k0, qf[0], negm, 0, 0, 0); p1 = __builtin_amdgcn_mfma_f32_32x32x16_bf16(k1, qf[0], negm, 0, 0, 0); }
;             else { p0 = __builtin_amdgcn_mfma_f32_32x32x16_bf16(k0, qf[ks], p0, 0, 0, 0); p1 = __builtin_amdgcn_mfma_f32_32x32x16_bf16(k1, qf[ks], p1, 0, 0, 0); }
;         }
;         if (BIAS) {
;             asm volatile("s_nop 15\n\ts_nop 7" : "+v"(p0), "+v"(p1));
;             const float d0 = qp - (float)(t * 64 + 4 * hi);
; #pragma unroll
;             for (int r = 0; r < 16; ++r) { const float dk = d0 - (float)((r & 3) + 8 * (r >> 2)); p0[r] = p0[r] - sl2 * fabsf(dk); p1[r] = p1[r] - sl2 * fabsf(dk - 32.f); }
;         } else {
;             asm volatile("s_nop 15\n\ts_nop 7" : "+v"(p0), "+v"(p1));
;         }
;         float mxa = max3f(p0[0], p0[1], p1[0]), mxb = max3f(p0[2], p0[3], p1[1]); mxa = max3f(mxa, p1[2], p1[3]);
; #pragma unroll
;         for (int r = 4; r < 16; r += 4) { mxa = max3f(mxa, p0[r], p0[r + 1]); mxb = max3f(mxb, p0[r + 2], p0[r + 3]); mxa = max3f(mxa, p1[r], p1[r + 1]); mxb = max3f(mxb, p1[r + 2], p1[r + 3]); }
;         float mx = fmaxf(mxa, mxb);
;         if (__any(mx > 8.f)) {
;     ...
;             float ls = 0.f;
; #pragma unroll
;             for (int hs = 0; hs < 4; ++hs) {
;                 float e[8];
; #pragma unroll
;                 for (int j = 0; j < 8; ++j) { e[j] = __builtin_amdgcn_exp2f(hs < 2 ? p0[8 * (hs & 1) + j] : p1[8 * (hs & 1) + j]); ls += e[j]; }
.Lend1_p4a1:
	s_cmp_eq_u32 s6, 0x1876000
	s_barrier
	s_cbranch_scc1 .LBB0_584
	s_andn2_b64 vcc, exec, s[44:45]
	s_waitcnt vmcnt(0)
	ds_write_b128 v168, v[138:141]
	ds_write_b128 v171, v[130:133] offset:18432
	ds_write_b128 v171, v[134:137] offset:26624
	s_cbranch_vccnz .LBB0_584
	s_add_u32 s100, s6, 0x12f000
	s_addc_u32 s101, s7, 0
	s_add_u32 s100, s100, s16
	s_addc_u32 s101, s101, s17
	global_load_dwordx4 v[130:133], v230, s[100:101] offset:2048
	global_load_dwordx4 v[134:137], v231, s[100:101] offset:2048
	s_add_u32 s100, s100, s98
	s_addc_u32 s101, s101, s99
	global_load_dwordx4 v[138:141], v232, s[100:101] offset:1024
.LBB0_584:
	ds_read_b128 v[192:195], v175 offset:9216
	ds_read_b128 v[196:199], v175 offset:9248
	v_add_f32_e32 v156, v157, v156
	v_add_f32_e32 v156, v160, v156
	s_waitcnt lgkmcnt(1)
	v_mfma_f32_32x32x16_bf16 v[98:113], v[192:195], v[114:117], v[66:81]
	ds_read_b128 v[192:195], v175 offset:13824
	ds_read_b128 v[200:203], v175 offset:13856
	v_add_f32_e32 v156, v161, v156
	v_add_f32_e32 v156, v164, v156
	v_add_f32_e32 v150, v150, v156
	v_add_f32_e32 v150, v165, v150
	v_add_f32_e32 v150, v166, v150
	v_add_f32_e32 v150, v167, v150
	s_waitcnt lgkmcnt(1)
	v_mfma_f32_32x32x16_bf16 v[82:97], v[192:195], v[114:117], v[66:81]
	v_add_f32_e32 v150, v177, v150
	v_add_f32_e32 v150, v178, v150
	v_add_f32_e32 v150, v158, v150
	v_add_f32_e32 v150, v159, v150
	ds_read_b128 v[164:167], v175 offset:9280
	v_add_f32_e32 v150, v162, v150
	v_add_f32_e32 v150, v163, v150
	v_mfma_f32_32x32x16_bf16 v[98:113], v[196:199], v[118:121], v[98:113]
	v_add_f32_e32 v150, v179, v150
	v_add_f32_e32 v150, v180, v150
	v_add_f32_e32 v150, v181, v150
	v_add_f32_e32 v150, v152, v150
	ds_read_b128 v[156:159], v175 offset:13888
	ds_read_b128 v[160:163], v175 offset:9312
	v_add_f32_e32 v150, v153, v150
	v_add_f32_e32 v150, v182, v150
	s_waitcnt lgkmcnt(3)
	v_mfma_f32_32x32x16_bf16 v[82:97], v[200:203], v[118:121], v[82:97]
	v_add_f32_e32 v150, v183, v150
	v_add_f32_e32 v150, v154, v150
	v_add_f32_e32 v150, v155, v150
	v_add_f32_e32 v150, v184, v150
	v_add_f32_e32 v150, v185, v150
	v_add_u32_e32 v152, 64, v173
	v_add_f32_e32 v150, v186, v150
	s_waitcnt lgkmcnt(2)
	v_mfma_f32_32x32x16_bf16 v[98:113], v[164:167], v[122:125], v[98:113]
	ds_read_b128 v[164:167], v175 offset:13920
	v_cvt_f32_u32_e32 v152, v152
	v_add_f32_e32 v150, v187, v150
	v_add_f32_e32 v150, v188, v150
	v_add_f32_e32 v150, v191, v150
	v_add_f32_e32 v150, v189, v150
	v_add_f32_e32 v150, v190, v150
	s_waitcnt lgkmcnt(2)
	v_mfma_f32_32x32x16_bf16 v[82:97], v[156:159], v[122:125], v[82:97]
	v_add_f32_e32 v158, v151, v150
	s_waitcnt lgkmcnt(1)
	v_mfma_f32_32x32x16_bf16 v[98:113], v[160:163], v[126:129], v[98:113]
	v_sub_f32_e32 v160, v172, v152
	v_add_f32_e32 v161, -1.0, v160
	s_waitcnt lgkmcnt(0)
	v_mfma_f32_32x32x16_bf16 v[82:97], v[164:167], v[126:129], v[82:97]
	s_nop 15
	s_nop 7
	s_nop 5
	v_fma_f32 v150, -v142, |v160|, v98
	v_fma_f32 v151, -v143, |v161|, v99
	v_pk_add_f32 v[98:99], v[160:161], s[8:9] op_sel_hi:[1,0]
	s_nop 0
	v_fma_f32 v83, -v143, |v99|, v83
	v_fma_f32 v82, -v142, |v98|, v82
	s_nop 0
	v_pk_add_f32 v[98:99], v[160:161], s[10:11] op_sel_hi:[0,1]
	v_fma_f32 v153, -v143, |v99|, v101
	v_fma_f32 v152, -v142, |v98|, v100
	v_pk_add_f32 v[98:99], v[98:99], s[8:9] op_sel_hi:[1,0]
	v_fma_f32 v99, -v143, |v99|, v85
	v_fma_f32 v98, -v142, |v98|, v84
	v_pk_add_f32 v[84:85], v[160:161], s[22:23] op_sel_hi:[0,1]
	v_fma_f32 v155, -v143, |v85|, v103
	v_fma_f32 v154, -v142, |v84|, v102
	v_pk_add_f32 v[84:85], v[84:85], s[8:9] op_sel_hi:[1,0]
	v_fma_f32 v101, -v143, |v85|, v87
	v_fma_f32 v100, -v142, |v84|, v86
	v_pk_add_f32 v[84:85], v[160:161], s[34:35] op_sel_hi:[0,1]
	v_fma_f32 v157, -v143, |v85|, v105
	v_fma_f32 v156, -v142, |v84|, v104
	v_pk_add_f32 v[84:85], v[84:85], s[8:9] op_sel_hi:[1,0]
	v_fma_f32 v103, -v143, |v85|, v89
	v_fma_f32 v102, -v142, |v84|, v88
	v_pk_add_f32 v[84:85], v[160:161], s[36:37] op_sel_hi:[0,1]
	v_fma_f32 v105, -v143, |v85|, v107
	v_fma_f32 v104, -v142, |v84|, v106
	v_pk_add_f32 v[86:87], v[160:161], s[38:39] op_sel_hi:[0,1]
	v_pk_add_f32 v[84:85], v[84:85], s[8:9] op_sel_hi:[1,0]
	v_fma_f32 v107, -v143, |v87|, v109
	v_fma_f32 v106, -v142, |v86|, v108
	v_fma_f32 v85, -v143, |v85|, v91
	v_fma_f32 v84, -v142, |v84|, v90
	v_pk_add_f32 v[86:87], v[86:87], s[8:9] op_sel_hi:[1,0]
	v_pk_add_f32 v[88:89], v[160:161], s[40:41] op_sel_hi:[0,1]
	v_fma_f32 v87, -v143, |v87|, v93
	v_fma_f32 v86, -v142, |v86|, v92
	v_fma_f32 v93, -v143, |v89|, v111
	v_fma_f32 v92, -v142, |v88|, v110
	v_pk_add_f32 v[88:89], v[88:89], s[8:9] op_sel_hi:[1,0]
	v_fma_f32 v89, -v143, |v89|, v95
	v_fma_f32 v88, -v142, |v88|, v94
	v_pk_add_f32 v[90:91], v[160:161], s[42:43] op_sel_hi:[0,1]
	v_fma_f32 v95, -v143, |v91|, v113
	v_fma_f32 v94, -v142, |v90|, v112
	v_pk_add_f32 v[90:91], v[90:91], s[8:9] op_sel_hi:[1,0]
	v_fma_f32 v91, -v143, |v91|, v97
	v_fma_f32 v90, -v142, |v90|, v96
	v_max3_f32 v96, v150, v151, v82
	v_max3_f32 v97, v152, v153, v83
	v_max3_f32 v96, v96, v98, v99
	v_max3_f32 v97, v97, v156, v157
	v_max3_f32 v96, v96, v154, v155
	v_max3_f32 v97, v97, v102, v103
	v_max3_f32 v96, v96, v100, v101
	v_max3_f32 v97, v97, v106, v107
	v_max3_f32 v96, v96, v104, v105
	v_max3_f32 v97, v97, v86, v87
	v_max3_f32 v96, v96, v84, v85
	v_max3_f32 v97, v97, v94, v95
	v_max3_f32 v96, v96, v92, v93
	v_max3_f32 v97, v97, v90, v91
	v_max3_f32 v96, v96, v88, v89
	v_max_f32_e32 v96, v96, v97
	v_cmp_gt_f32_e32 vcc, 0xc3400000, v96
	s_cmp_eq_u64 vcc, exec
	s_cbranch_scc1 .Lsk2_p4a1
; template <int DQK, int DV, bool BIAS> ...
;     ...
;         if (__any(mx > 8.f)) {
;             mx = fmaxf(mx, __shfl_xor(mx, 32));
;             const float dl = fmaxf(mx, 0.f); mhat += dl;
;             const float f = __builtin_amdgcn_exp2f(-dl);
; #pragma unroll
;             for (int r = 0; r < 16; ++r) { p0[r] -= dl; p1[r] -= dl; negm[r] = -mhat; }
;             l *= f;
; #pragma unroll
;             for (int d = 0; d < NDT; ++d)
; #pragma unroll
;                 for (int r = 0; r < 16; ++r) o[d][r] *= f;
;         }
	v_cmp_lt_f32_e32 vcc, s52, v96
	s_cbranch_vccz .LBB0_575
	v_and_b32_e32 v67, 64, v170
	v_xor_b32_e32 v66, 32, v170
	v_add_u32_e32 v67, 64, v67
	v_cmp_lt_i32_e32 vcc, v66, v67
	s_nop 1
	v_cndmask_b32_e32 v66, v170, v66, vcc
	v_lshlrev_b32_e32 v66, 2, v66
	ds_bpermute_b32 v66, v66, v96
	s_waitcnt lgkmcnt(0)
	v_max3_f32 v67, v96, v66, 0
	v_exp_f32_e64 v68, -v67
	v_add_f32_e32 v176, v176, v67
	v_xor_b32_e32 v66, 0x80000000, v176
	v_sub_f32_e32 v82, v82, v67
	v_sub_f32_e32 v83, v83, v67
	v_sub_f32_e32 v98, v98, v67
	v_sub_f32_e32 v99, v99, v67
	v_sub_f32_e32 v100, v100, v67
	v_sub_f32_e32 v101, v101, v67
	v_sub_f32_e32 v102, v102, v67
	v_sub_f32_e32 v103, v103, v67
	v_sub_f32_e32 v84, v84, v67
	v_sub_f32_e32 v85, v85, v67
	v_sub_f32_e32 v86, v86, v67
	v_sub_f32_e32 v87, v87, v67
	v_sub_f32_e32 v88, v88, v67
	v_sub_f32_e32 v89, v89, v67
	v_sub_f32_e32 v90, v90, v67
	v_sub_f32_e32 v91, v91, v67
	v_pk_mul_f32 v[64:65], v[64:65], v[68:69] op_sel_hi:[1,0]
	v_pk_mul_f32 v[62:63], v[62:63], v[68:69] op_sel_hi:[1,0]
	v_pk_mul_f32 v[60:61], v[60:61], v[68:69] op_sel_hi:[1,0]
	v_pk_mul_f32 v[58:59], v[58:59], v[68:69] op_sel_hi:[1,0]
	v_pk_mul_f32 v[56:57], v[56:57], v[68:69] op_sel_hi:[1,0]
	v_pk_mul_f32 v[54:55], v[54:55], v[68:69] op_sel_hi:[1,0]
	v_pk_mul_f32 v[52:53], v[52:53], v[68:69] op_sel_hi:[1,0]
	v_pk_mul_f32 v[50:51], v[50:51], v[68:69] op_sel_hi:[1,0]
	v_pk_mul_f32 v[48:49], v[48:49], v[68:69] op_sel_hi:[1,0]
	v_pk_mul_f32 v[46:47], v[46:47], v[68:69] op_sel_hi:[1,0]
	v_pk_mul_f32 v[44:45], v[44:45], v[68:69] op_sel_hi:[1,0]
	v_pk_mul_f32 v[42:43], v[42:43], v[68:69] op_sel_hi:[1,0]
	v_pk_mul_f32 v[40:41], v[40:41], v[68:69] op_sel_hi:[1,0]
	v_pk_mul_f32 v[38:39], v[38:39], v[68:69] op_sel_hi:[1,0]
	v_pk_mul_f32 v[36:37], v[36:37], v[68:69] op_sel_hi:[1,0]
	v_pk_mul_f32 v[34:35], v[34:35], v[68:69] op_sel_hi:[1,0]
	v_pk_mul_f32 v[32:33], v[32:33], v[68:69] op_sel_hi:[1,0]
	v_pk_mul_f32 v[30:31], v[30:31], v[68:69] op_sel_hi:[1,0]
	v_pk_mul_f32 v[28:29], v[28:29], v[68:69] op_sel_hi:[1,0]
	v_pk_mul_f32 v[26:27], v[26:27], v[68:69] op_sel_hi:[1,0]
	v_pk_mul_f32 v[24:25], v[24:25], v[68:69] op_sel_hi:[1,0]
	v_pk_mul_f32 v[22:23], v[22:23], v[68:69] op_sel_hi:[1,0]
	v_pk_mul_f32 v[20:21], v[20:21], v[68:69] op_sel_hi:[1,0]
	v_pk_mul_f32 v[18:19], v[18:19], v[68:69] op_sel_hi:[1,0]
	v_pk_mul_f32 v[16:17], v[16:17], v[68:69] op_sel_hi:[1,0]
	v_pk_mul_f32 v[14:15], v[14:15], v[68:69] op_sel_hi:[1,0]
	v_pk_mul_f32 v[12:13], v[12:13], v[68:69] op_sel_hi:[1,0]
	v_pk_mul_f32 v[10:11], v[10:11], v[68:69] op_sel_hi:[1,0]
	v_pk_mul_f32 v[8:9], v[8:9], v[68:69] op_sel_hi:[1,0]
	v_pk_mul_f32 v[6:7], v[6:7], v[68:69] op_sel_hi:[1,0]
	v_pk_mul_f32 v[4:5], v[4:5], v[68:69] op_sel_hi:[1,0]
	v_pk_mul_f32 v[2:3], v[2:3], v[68:69] op_sel_hi:[1,0]
	v_sub_f32_e32 v150, v150, v67
	v_sub_f32_e32 v151, v151, v67
	v_sub_f32_e32 v152, v152, v67
	v_sub_f32_e32 v153, v153, v67
	v_sub_f32_e32 v154, v154, v67
	v_sub_f32_e32 v155, v155, v67
	v_sub_f32_e32 v156, v156, v67
	v_sub_f32_e32 v157, v157, v67
	v_sub_f32_e32 v104, v104, v67
	v_sub_f32_e32 v105, v105, v67
	v_sub_f32_e32 v106, v106, v67
	v_sub_f32_e32 v107, v107, v67
	v_sub_f32_e32 v92, v92, v67
	v_sub_f32_e32 v93, v93, v67
	v_sub_f32_e32 v94, v94, v67
	v_sub_f32_e32 v95, v95, v67
	v_mul_f32_e32 v158, v158, v68
	v_mov_b32_e32 v67, v66
	v_mov_b32_e32 v68, v66
	v_mov_b32_e32 v69, v66
	v_mov_b32_e32 v70, v66
	v_mov_b32_e32 v71, v66
	v_mov_b32_e32 v72, v66
	v_mov_b32_e32 v73, v66
	v_mov_b32_e32 v74, v66
	v_mov_b32_e32 v75, v66
	v_mov_b32_e32 v76, v66
	v_mov_b32_e32 v77, v66
	v_mov_b32_e32 v78, v66
	v_mov_b32_e32 v79, v66
	v_mov_b32_e32 v80, v66
	v_mov_b32_e32 v81, v66
	s_branch .LBB0_575

; template <int DQK, int DV, bool BIAS> ...
;     ...
;     for (int ks = 0; ks < NKS; ++ks) qf[ks] = ks < 4 ? *(const bf16x8*)(Qw + (size_t)r32 * ldq + ks * 16 + hi * 8) : *(const bf16x8*)(Q2w + (size_t)r32 * ldq2 + (ks - 4) * 16 + hi * 8);
; #pragma unroll
;     for (int ks = 0; ks < 4; ++ks) qf[ks] = scale_frag(qf[ks], cs);
;     if constexpr (DQK == 96) {
;         const float* rp = ropetab + ((size_t)(qpos0 + r32) * 16) * 2;
; #pragma unroll
;         for (int ks = 4; ks < 6; ++ks) {
;             const f32x4 c0 = *(const f32x4*)(rp + ((ks - 4) * 8 + hi * 4) * 2), c1 = *(const f32x4*)(rp + ((ks - 4) * 8 + hi * 4 + 2) * 2);
;             const u32x4 w = __builtin_bit_cast(u32x4, qf[ks]); u32x4 ow;
;     ...
;     l += __shfl_xor(l, 32);
;     const float inv = 1.f / l;
; #pragma unroll
;     for (int d = 0; d < NDT; ++d)
; #pragma unroll
;         for (int r = 0; r < 16; ++r) o[d][r] *= inv;
; }
; template <int NDT> __device__ __forceinline__ void attn_store(const f32x16 (&o)[NDT], bf16_t* Ow, int ldo, int r32, int hi) {
; #pragma unroll
;     for (int d = 0; d < NDT; ++d)
; #pragma unroll
;         for (int q = 0; q < 4; ++q) { u32x2 w; w.x = cvtpk(o[d][4 * q], o[d][4 * q + 1]); w.y = cvtpk(o[d][4 * q + 2], o[d][4 * q + 3]); *(u32x2*)(Ow + (size_t)r32 * ldo + 32 * d + 8 * q + 4 * hi) = w; }
; }
; __device__ __forceinline__ void attn_phase(PPtr P, int li, LAS unsigned char* lds, int vcu, int wave, int lane) {
;     bf16_t* proj = (bf16_t*)(P->ws + OFF_PROJ); bf16_t* mlaq = (bf16_t*)(P->ws + OFF_MLAQ); const bf16_t* mlakv = (const bf16_t*)(P->ws + OFF_MLAKV);
;     const int r32 = lane & 31, hi = lane >> 5;
;     {
;         const int b = vcu >> 6, h = (vcu >> 4) & 3, qb = vcu & 15;
;         const size_t seq0 = (size_t)b * SEQL, qrow = seq0 + qb * 256 + wave * 32;
;         const float slope = __builtin_amdgcn_exp2f(-2.f * (float)(h + 1));
;         f32x16 o1[4], o2[4];
;         attn_pass<64, 128, true>(lds, proj + qrow * LDP + C_AQ + h * 128, LDP, nullptr, 0, proj + seq0 * LDP + C_AK + h * 128, LDP, nullptr, 0, proj + seq0 * LDP + C_AV + h * 128, LDP, qb * 256 + wave * 32, 0.125f * LOG2E, slope * LOG2E, nullptr, o1);
;         LAS unsigned* o1s = (LAS unsigned*)(lds + 81920 + wave * 8192) + lane;
; #pragma unroll
;         for (int d = 0; d < 4; ++d)
; #pragma unroll
;             for (int r = 0; r < 8; ++r) o1s[(d * 8 + r) * 64] = cvtpk(o1[d][2 * r], o1[d][2 * r + 1]);
.LBB0_586:
	v_and_b32_e32 v67, 64, v170
	v_xor_b32_e32 v66, 32, v170
	v_add_u32_e32 v172, 64, v67
	v_cmp_lt_i32_e32 vcc, v66, v172
	v_and_b32_e32 v173, 63, v169
	s_nop 0
	v_cndmask_b32_e32 v66, v170, v66, vcc
	v_lshlrev_b32_e32 v168, 2, v66
	ds_bpermute_b32 v66, v168, v151
	s_barrier
	s_waitcnt lgkmcnt(0)
	s_movk_i32 s8, 0x1940
	s_mov_b32 s10, 0xc1000000
	v_add_f32_e32 v66, v151, v66
	v_div_scale_f32 v67, s[6:7], v66, v66, 1.0
	v_rcp_f32_e32 v68, v67
	s_lshl_b32 s6, s50, 13
	s_add_i32 s6, s6, 0
	v_mov_b32_e32 v151, 0
	v_fma_f32 v69, -v67, v68, 1.0
	v_fmac_f32_e32 v68, v69, v68
	v_div_scale_f32 v69, vcc, 1.0, v66, 1.0
	v_mul_f32_e32 v70, v69, v68
	v_fma_f32 v71, -v67, v70, v69
	v_fmac_f32_e32 v70, v71, v68
	v_fma_f32 v67, -v67, v70, v69
	v_div_fmas_f32 v67, v67, v68, v70
	v_div_fixup_f32 v66, v67, v66, 1.0
	v_pk_mul_f32 v[50:51], v[50:51], v[66:67] op_sel_hi:[1,0]
	v_pk_mul_f32 v[52:53], v[52:53], v[66:67] op_sel_hi:[1,0]
	v_pk_mul_f32 v[54:55], v[54:55], v[66:67] op_sel_hi:[1,0]
	v_pk_mul_f32 v[56:57], v[56:57], v[66:67] op_sel_hi:[1,0]
	v_pk_mul_f32 v[58:59], v[58:59], v[66:67] op_sel_hi:[1,0]
	v_pk_mul_f32 v[60:61], v[60:61], v[66:67] op_sel_hi:[1,0]
	v_pk_mul_f32 v[62:63], v[62:63], v[66:67] op_sel_hi:[1,0]
	v_pk_mul_f32 v[64:65], v[64:65], v[66:67] op_sel_hi:[1,0]
	v_pk_mul_f32 v[34:35], v[34:35], v[66:67] op_sel_hi:[1,0]
	v_pk_mul_f32 v[36:37], v[36:37], v[66:67] op_sel_hi:[1,0]
	v_pk_mul_f32 v[38:39], v[38:39], v[66:67] op_sel_hi:[1,0]
	v_pk_mul_f32 v[40:41], v[40:41], v[66:67] op_sel_hi:[1,0]
	v_pk_mul_f32 v[42:43], v[42:43], v[66:67] op_sel_hi:[1,0]
	v_pk_mul_f32 v[44:45], v[44:45], v[66:67] op_sel_hi:[1,0]
	v_pk_mul_f32 v[46:47], v[46:47], v[66:67] op_sel_hi:[1,0]
	v_pk_mul_f32 v[48:49], v[48:49], v[66:67] op_sel_hi:[1,0]
	v_pk_mul_f32 v[18:19], v[18:19], v[66:67] op_sel_hi:[1,0]
	v_pk_mul_f32 v[20:21], v[20:21], v[66:67] op_sel_hi:[1,0]
	v_pk_mul_f32 v[22:23], v[22:23], v[66:67] op_sel_hi:[1,0]
	v_pk_mul_f32 v[24:25], v[24:25], v[66:67] op_sel_hi:[1,0]
	v_pk_mul_f32 v[26:27], v[26:27], v[66:67] op_sel_hi:[1,0]
	v_pk_mul_f32 v[28:29], v[28:29], v[66:67] op_sel_hi:[1,0]
	v_pk_mul_f32 v[30:31], v[30:31], v[66:67] op_sel_hi:[1,0]
	v_pk_mul_f32 v[32:33], v[32:33], v[66:67] op_sel_hi:[1,0]
	v_pk_mul_f32 v[2:3], v[2:3], v[66:67] op_sel_hi:[1,0]
	v_pk_mul_f32 v[4:5], v[4:5], v[66:67] op_sel_hi:[1,0]
	v_pk_mul_f32 v[6:7], v[6:7], v[66:67] op_sel_hi:[1,0]
	v_pk_mul_f32 v[8:9], v[8:9], v[66:67] op_sel_hi:[1,0]
	v_pk_mul_f32 v[10:11], v[10:11], v[66:67] op_sel_hi:[1,0]
	v_pk_mul_f32 v[12:13], v[12:13], v[66:67] op_sel_hi:[1,0]
	v_pk_mul_f32 v[14:15], v[14:15], v[66:67] op_sel_hi:[1,0]
	v_pk_mul_f32 v[16:17], v[16:17], v[66:67] op_sel_hi:[1,0]
	v_lshl_add_u32 v66, v173, 2, s6
	v_add_u32_e32 v171, 0x14000, v66
	v_cvt_pk_bf16_f32 v50, v50, v51
	v_cvt_pk_bf16_f32 v51, v52, v53
	v_cvt_pk_bf16_f32 v34, v34, v35
	v_cvt_pk_bf16_f32 v35, v36, v37
	v_cvt_pk_bf16_f32 v18, v18, v19
	v_cvt_pk_bf16_f32 v19, v20, v21
	v_cvt_pk_bf16_f32 v2, v2, v3
	v_cvt_pk_bf16_f32 v3, v4, v5
	ds_write2st64_b32 v171, v50, v51 offset1:1
	v_cvt_pk_bf16_f32 v50, v54, v55
	v_cvt_pk_bf16_f32 v51, v56, v57
	ds_write2st64_b32 v171, v34, v35 offset0:8 offset1:9
	v_cvt_pk_bf16_f32 v34, v38, v39
	v_cvt_pk_bf16_f32 v35, v40, v41
	ds_write2st64_b32 v171, v18, v19 offset0:16 offset1:17
	v_cvt_pk_bf16_f32 v18, v22, v23
	v_cvt_pk_bf16_f32 v19, v24, v25
	ds_write2st64_b32 v171, v2, v3 offset0:24 offset1:25
	v_cvt_pk_bf16_f32 v2, v6, v7
	v_cvt_pk_bf16_f32 v3, v8, v9
	ds_write2st64_b32 v171, v50, v51 offset0:2 offset1:3
	v_cvt_pk_bf16_f32 v50, v58, v59
	v_cvt_pk_bf16_f32 v51, v60, v61
	ds_write2st64_b32 v171, v34, v35 offset0:10 offset1:11
	v_cvt_pk_bf16_f32 v34, v42, v43
	v_cvt_pk_bf16_f32 v35, v44, v45
	ds_write2st64_b32 v171, v18, v19 offset0:18 offset1:19
	v_cvt_pk_bf16_f32 v18, v26, v27
	v_cvt_pk_bf16_f32 v19, v28, v29
	ds_write2st64_b32 v171, v2, v3 offset0:26 offset1:27
	v_cvt_pk_bf16_f32 v2, v10, v11
	v_cvt_pk_bf16_f32 v3, v12, v13
	ds_write2st64_b32 v171, v50, v51 offset0:4 offset1:5
	v_cvt_pk_bf16_f32 v50, v62, v63
	v_cvt_pk_bf16_f32 v51, v64, v65
	ds_write2st64_b32 v171, v34, v35 offset0:12 offset1:13
	v_cvt_pk_bf16_f32 v34, v46, v47
	v_cvt_pk_bf16_f32 v35, v48, v49
	ds_write2st64_b32 v171, v18, v19 offset0:20 offset1:21
	v_cvt_pk_bf16_f32 v18, v30, v31
	v_cvt_pk_bf16_f32 v19, v32, v33
	ds_write2st64_b32 v171, v2, v3 offset0:28 offset1:29
	v_cvt_pk_bf16_f32 v2, v14, v15
	v_cvt_pk_bf16_f32 v3, v16, v17
	v_mov_b32_e32 v22, v1
	ds_write2st64_b32 v171, v50, v51 offset0:6 offset1:7
	ds_write2st64_b32 v171, v34, v35 offset0:14 offset1:15
	ds_write2st64_b32 v171, v18, v19 offset0:22 offset1:23
	ds_write2st64_b32 v171, v2, v3 offset0:30 offset1:31
	s_mov_b32 s6, 0x3e38aa3b
	v_and_b32_e32 v23, 31, v22
	v_mul_u32_u24_e32 v2, 0xca0, v23
	v_bfe_u32 v24, v22, 5, 1
	v_lshlrev_b32_e32 v150, 1, v2
	v_lshl_add_u64 v[2:3], s[18:19], 0, v[150:151]
	v_lshlrev_b32_e32 v150, 4, v24
	v_lshl_add_u64 v[18:19], v[2:3], 0, v[150:151]
	global_load_dwordx4 v[2:5], v[18:19], off offset:128
	global_load_dwordx4 v[6:9], v[18:19], off offset:160
	global_load_dwordx4 v[10:13], v[18:19], off offset:192
	global_load_dwordx4 v[14:17], v[18:19], off offset:224
	v_ashrrev_i32_e32 v25, 3, v22
	v_lshlrev_b32_e32 v26, 4, v22
	v_lshrrev_b32_e32 v28, 2, v22
	v_lshlrev_b32_e32 v177, 2, v24
	v_and_b32_e32 v29, 0xfc0, v26
	v_and_b32_e32 v30, 48, v26
	v_mov_b32_e32 v50, v151
	v_mov_b32_e32 v51, v151
	v_mov_b32_e32 v52, v151
	v_mov_b32_e32 v53, v151
	v_mov_b32_e32 v54, v151
	v_mov_b32_e32 v55, v151
	v_mov_b32_e32 v56, v151
	v_mov_b32_e32 v57, v151
	v_mov_b32_e32 v58, v151
	v_mov_b32_e32 v59, v151
	v_mov_b32_e32 v60, v151
	v_mov_b32_e32 v61, v151
	v_mov_b32_e32 v62, v151
	v_mov_b32_e32 v63, v151
	v_mov_b32_e32 v64, v151
	v_mov_b32_e32 v65, v151
	s_mov_b32 s22, 0xc1200000
	s_mov_b32 s34, 0xc1800000
	s_mov_b32 s36, 0xc1900000
	s_mov_b32 s38, 0xc1c00000
	s_mov_b32 s40, 0xc1d00000
	v_mov_b64_e32 v[34:35], v[50:51]
	s_mov_b32 s11, 0xc1100000
	s_mov_b32 s23, 0xc1300000
	s_mov_b32 s35, 0xc1880000
	s_mov_b32 s37, 0xc1980000
	s_mov_b32 s39, 0xc1c80000
	s_mov_b32 s41, 0xc1d80000
	s_mov_b32 s44, 0x41000000
	v_mov_b64_e32 v[36:37], v[52:53]
	v_mov_b64_e32 v[38:39], v[54:55]
	v_mov_b64_e32 v[40:41], v[56:57]
	v_mov_b64_e32 v[42:43], v[58:59]
	v_mov_b64_e32 v[44:45], v[60:61]
	v_mov_b64_e32 v[46:47], v[62:63]
	v_mov_b64_e32 v[48:49], v[64:65]
	v_mov_b32_e32 v180, v151
	v_mov_b32_e32 v66, v151
	v_mov_b32_e32 v67, v151
	v_mov_b32_e32 v68, v151
	v_mov_b32_e32 v69, v151
	v_mov_b32_e32 v70, v151
	v_mov_b32_e32 v71, v151
	v_mov_b32_e32 v72, v151
	v_mov_b32_e32 v73, v151
	v_mov_b32_e32 v74, v151
	v_mov_b32_e32 v75, v151
	v_mov_b32_e32 v76, v151
	v_mov_b32_e32 v77, v151
	v_mov_b32_e32 v78, v151
	v_mov_b32_e32 v79, v151
	v_mov_b32_e32 v80, v151
	v_mov_b32_e32 v81, v151
	s_waitcnt vmcnt(3)
; __device__ __forceinline__ unsigned cvtpk(float lo, float hi) { typedef __bf16 bf2 __attribute__((ext_vector_type(2))); f32x2 v = {lo, hi}; bf2 b = __builtin_convertvector(v, bf2); return __builtin_bit_cast(unsigned, b); }
; template <int DQK, int DV, bool BIAS> ...
;     ...
;     for (int ks = 0; ks < NKS; ++ks) qf[ks] = ks < 4 ? *(const bf16x8*)(Qw + (size_t)r32 * ldq + ks * 16 + hi * 8) : *(const bf16x8*)(Q2w + (size_t)r32 * ldq2 + (ks - 4) * 16 + hi * 8);
; #pragma unroll
;     for (int ks = 0; ks < 4; ++ks) qf[ks] = scale_frag(qf[ks], cs);
;     if constexpr (DQK == 96) {
;         const float* rp = ropetab + ((size_t)(qpos0 + r32) * 16) * 2;
; #pragma unroll
;         for (int ks = 4; ks < 6; ++ks) {
;             const f32x4 c0 = *(const f32x4*)(rp + ((ks - 4) * 8 + hi * 4) * 2), c1 = *(const f32x4*)(rp + ((ks - 4) * 8 + hi * 4 + 2) * 2);
;             const u32x4 w = __builtin_bit_cast(u32x4, qf[ks]); u32x4 ow;
;             { const float a = bflo(w.x) * cs, b = bfhi(w.x) * cs; ow.x = cvtpk(a * c0[0] - b * c0[1], a * c0[1] + b * c0[0]); }
;             { const float a = bflo(w.y) * cs, b = bfhi(w.y) * cs; ow.y = cvtpk(a * c0[2] - b * c0[3], a * c0[3] + b * c0[2]); }
;             { const float a = bflo(w.z) * cs, b = bfhi(w.z) * cs; ow.z = cvtpk(a * c1[0] - b * c1[1], a * c1[1] + b * c1[0]); }
;             { const float a = bflo(w.w) * cs, b = bfhi(w.w) * cs; ow.w = cvtpk(a * c1[2] - b * c1[3], a * c1[3] + b * c1[2]); }
;             qf[ks] = __builtin_bit_cast(bf16x8, ow);
;         }
;     }
; #pragma unroll
;     for (int d = 0; d < NDT; ++d)
; #pragma unroll
;         for (int r = 0; r < 16; ++r) o[d][r] = 0.f;
; #pragma unroll
;     for (int ks = 0; ks < NKS; ++ks) asm volatile("" : "+v"(qf[ks]));
;     float mhat = 0.f, l = 0.f; f32x16 negm;
; #pragma unroll
;     for (int r = 0; r < 16; ++r) negm[r] = 0.f;
;     constexpr int TPB = (DV == 64) ? 2 : 1, NG = SEQL / 64 / TPB;
;     u32x4 kreg[TPB], k2reg[TPB], vreg[TPB][NVL];
;     const bf16_t* kptr = Kg + (size_t)(tid >> 3) * ldk + (tid & 7) * 8;
;     const bf16_t* k2ptr = (DQK == 96) ? K2g + (size_t)(tid >> 2) * ldk2 + (tid & 3) * 8 : nullptr;
;     ...
;     u32x4 pw[4];
; #pragma unroll
;     for (int j = 0; j < TPB; ++j) { ATT_LOAD(j, j); ATT_STORE(j, j); }
; #pragma unroll
;     for (int j = 0; j < TPB; ++j) ATT_LOAD(TPB + j, j);
;     const float qp = (float)(qpos0 + r32);
	v_lshlrev_b32_e32 v18, 16, v2
	v_and_b32_e32 v19, 0xffff0000, v2
	v_lshlrev_b32_e32 v2, 16, v3
	v_and_b32_e32 v3, 0xffff0000, v3
	v_pk_mul_f32 v[2:3], v[2:3], s[6:7] op_sel_hi:[1,0]
	v_pk_mul_f32 v[18:19], v[18:19], s[6:7] op_sel_hi:[1,0]
	v_cvt_pk_bf16_f32 v115, v2, v3
	v_lshlrev_b32_e32 v2, 16, v4
	v_and_b32_e32 v3, 0xffff0000, v4
	v_pk_mul_f32 v[2:3], v[2:3], s[6:7] op_sel_hi:[1,0]
	v_cvt_pk_bf16_f32 v114, v18, v19
	v_cvt_pk_bf16_f32 v116, v2, v3
	v_lshlrev_b32_e32 v2, 16, v5
	v_and_b32_e32 v3, 0xffff0000, v5
	v_pk_mul_f32 v[2:3], v[2:3], s[6:7] op_sel_hi:[1,0]
	s_nop 0
	v_cvt_pk_bf16_f32 v117, v2, v3
	s_waitcnt vmcnt(2)
	v_lshlrev_b32_e32 v2, 16, v6
	v_and_b32_e32 v3, 0xffff0000, v6
	v_pk_mul_f32 v[2:3], v[2:3], s[6:7] op_sel_hi:[1,0]
	s_nop 0
	v_cvt_pk_bf16_f32 v118, v2, v3
	v_lshlrev_b32_e32 v2, 16, v7
	v_and_b32_e32 v3, 0xffff0000, v7
	v_pk_mul_f32 v[2:3], v[2:3], s[6:7] op_sel_hi:[1,0]
	s_nop 0
	v_cvt_pk_bf16_f32 v119, v2, v3
	v_lshlrev_b32_e32 v2, 16, v8
	v_and_b32_e32 v3, 0xffff0000, v8
	v_pk_mul_f32 v[2:3], v[2:3], s[6:7] op_sel_hi:[1,0]
	v_lshlrev_b32_e32 v8, 3, v22
	v_cvt_pk_bf16_f32 v120, v2, v3
	v_lshlrev_b32_e32 v2, 16, v9
	v_and_b32_e32 v3, 0xffff0000, v9
	v_pk_mul_f32 v[2:3], v[2:3], s[6:7] op_sel_hi:[1,0]
	v_and_b32_e32 v27, 24, v8
	v_cvt_pk_bf16_f32 v121, v2, v3
	s_waitcnt vmcnt(1)
	v_lshlrev_b32_e32 v2, 16, v10
	v_and_b32_e32 v3, 0xffff0000, v10
	v_pk_mul_f32 v[2:3], v[2:3], s[6:7] op_sel_hi:[1,0]
	v_add_u32_e32 v10, 0x200, v22
	v_cvt_pk_bf16_f32 v122, v2, v3
	v_lshlrev_b32_e32 v2, 16, v11
	v_and_b32_e32 v3, 0xffff0000, v11
	v_pk_mul_f32 v[2:3], v[2:3], s[6:7] op_sel_hi:[1,0]
	v_lshlrev_b32_e32 v8, 1, v27
	v_cvt_pk_bf16_f32 v123, v2, v3
	v_lshlrev_b32_e32 v2, 16, v12
	v_and_b32_e32 v3, 0xffff0000, v12
	v_pk_mul_f32 v[2:3], v[2:3], s[6:7] op_sel_hi:[1,0]
	v_mov_b32_e32 v9, v151
	v_cvt_pk_bf16_f32 v124, v2, v3
	v_lshlrev_b32_e32 v2, 16, v13
	v_and_b32_e32 v3, 0xffff0000, v13
	v_pk_mul_f32 v[2:3], v[2:3], s[6:7] op_sel_hi:[1,0]
	v_ashrrev_i32_e32 v10, 3, v10
	v_cvt_pk_bf16_f32 v125, v2, v3
	s_waitcnt vmcnt(0)
	v_lshlrev_b32_e32 v2, 16, v14
	v_and_b32_e32 v3, 0xffff0000, v14
	v_pk_mul_f32 v[2:3], v[2:3], s[6:7] op_sel_hi:[1,0]
	v_and_b32_e32 v14, 0x70, v26
	v_cvt_pk_bf16_f32 v126, v2, v3
	v_lshlrev_b32_e32 v2, 16, v15
	v_and_b32_e32 v3, 0xffff0000, v15
	v_pk_mul_f32 v[2:3], v[2:3], s[6:7] op_sel_hi:[1,0]
	v_mov_b32_e32 v15, v151
	v_cvt_pk_bf16_f32 v127, v2, v3
	v_lshlrev_b32_e32 v2, 16, v16
	v_and_b32_e32 v3, 0xffff0000, v16
	v_pk_mul_f32 v[2:3], v[2:3], s[6:7] op_sel_hi:[1,0]
	v_and_b32_e32 v10, 0xffffffe0, v10
	v_cvt_pk_bf16_f32 v128, v2, v3
	v_lshlrev_b32_e32 v2, 16, v17
	v_and_b32_e32 v3, 0xffff0000, v17
	v_pk_mul_f32 v[2:3], v[2:3], s[6:7] op_sel_hi:[1,0]
	v_ashrrev_i32_e32 v11, 31, v10
	v_cvt_pk_bf16_f32 v129, v2, v3
	v_mov_b64_e32 v[2:3], s[4:5]
	v_mad_i64_i32 v[2:3], s[6:7], v25, s8, v[2:3]
	v_lshl_add_u64 v[144:145], v[2:3], 0, v[14:15]
	v_subrev_u32_e32 v232, s4, v144
	s_sub_u32 s98, s4, s16
	s_subb_u32 s99, s5, s17
	v_bfe_u32 v15, v22, 2, 6
	v_mul_u32_u24_e32 v2, 0xca0, v15
	v_lshlrev_b32_e32 v2, 1, v2
	v_mov_b32_e32 v3, v151
	v_lshl_add_u64 v[6:7], s[4:5], 0, v[2:3]
	global_load_dwordx4 v[2:5], v[144:145], off offset:1152
	v_lshl_add_u64 v[16:17], v[6:7], 0, v[8:9]
	v_and_b32_e32 v6, 0xffffffe0, v25
	s_movk_i32 s6, 0x90
	v_ashrrev_i32_e32 v7, 31, v6
	v_mul_lo_u32 v25, v25, s6
	v_lshlrev_b64 v[18:19], 1, v[6:7]
	v_lshlrev_b64 v[20:21], 1, v[10:11]
	v_add_u32_e32 v25, 0, v25
	v_lshl_add_u64 v[6:7], v[16:17], 0, v[18:19]
	v_lshl_add_u64 v[10:11], v[16:17], 0, v[20:21]
	v_add_u32_e32 v174, v25, v14
	s_mov_b64 s[4:5], 0x65800
	global_load_dwordx4 v[6:9], v[6:7], off offset:2048
	v_add3_u32 v14, 0, v29, v30
	global_load_dwordx4 v[10:13], v[10:11], off offset:2048
	v_and_b32_e32 v25, 0xfffff000, v26
	v_add_u32_e32 v175, v14, v25
	s_mov_b32 s7, 0
	s_waitcnt vmcnt(2)
	ds_write_b128 v174, v[2:5]
	v_lshl_add_u64 v[2:3], v[16:17], 0, s[4:5]
	v_lshl_add_u64 v[4:5], v[2:3], 0, v[18:19]
	s_mov_b32 s4, 0x65000
	global_load_dwordx4 v[130:133], v[4:5], off
	v_lshl_add_u64 v[2:3], v[2:3], 0, v[20:21]
	v_add_co_u32_e32 v4, vcc, s4, v144
	s_add_u32 s4, s9, s49
	s_nop 0
	v_addc_co_u32_e32 v5, vcc, 0, v145, vcc
	global_load_dwordx4 v[134:137], v[2:3], off
	global_load_dwordx4 v[138:141], v[4:5], off offset:1152
	v_or_b32_e32 v2, s3, v23
	v_cvt_f32_i32_e32 v176, v2
	v_and_or_b32 v2, v28, 3, v177
	v_lshlrev_b32_e32 v3, 1, v22
	v_lshl_add_u32 v2, v2, 6, 0
	v_and_b32_e32 v3, 32, v3
	s_addc_u32 s5, 0, s48
	v_add3_u32 v178, v2, v3, v27
	v_mov_b64_e32 v[2:3], s[4:5]
	v_and_b32_e32 v4, 3, v22
	v_mad_u64_u32 v[2:3], s[4:5], v15, s8, v[2:3]
	v_lshlrev_b32_e32 v4, 4, v4
	v_mov_b32_e32 v5, v151
	v_lshl_add_u64 v[2:3], v[2:3], 0, v[4:5]
	s_waitcnt vmcnt(4)
	ds_write_b128 v175, v[6:9] offset:18432
	s_waitcnt vmcnt(3)
	ds_write_b128 v175, v[10:13] offset:26624
	v_mad_u32_u24 v6, v23, s6, 0
	v_lshl_add_u64 v[4:5], v[2:3], 0, v[20:21]
	v_lshl_add_u64 v[2:3], v[2:3], 0, v[18:19]
	v_mov_b32_e32 v231, v4
	v_lshl_add_u64 v[146:147], s[16:17], 0, v[4:5]
	v_mov_b32_e32 v230, v2
	v_lshl_add_u64 v[148:149], s[16:17], 0, v[2:3]
	s_mov_b32 s8, -2.0
	v_add_u32_e32 v179, v6, v150
	v_mov_b64_e32 v[18:19], v[50:51]
	v_mov_b64_e32 v[2:3], v[50:51]
	s_mov_b64 s[4:5], 0
	s_mov_b32 s6, 0xc2000000
	s_mov_b32 s9, 0xc0400000
	v_mov_b64_e32 v[20:21], v[52:53]
	v_mov_b64_e32 v[22:23], v[54:55]
	v_mov_b64_e32 v[24:25], v[56:57]
	v_mov_b64_e32 v[26:27], v[58:59]
	v_mov_b64_e32 v[28:29], v[60:61]
	v_mov_b64_e32 v[30:31], v[62:63]
	v_mov_b64_e32 v[32:33], v[64:65]
	v_mov_b64_e32 v[4:5], v[52:53]
	v_mov_b64_e32 v[6:7], v[54:55]
	v_mov_b64_e32 v[8:9], v[56:57]
	v_mov_b64_e32 v[10:11], v[58:59]
	v_mov_b64_e32 v[12:13], v[60:61]
	v_mov_b64_e32 v[14:15], v[62:63]
	v_mov_b64_e32 v[16:17], v[64:65]
	s_branch .LBB0_588

; #define LAS __attribute__((address_space(3)))
; __device__ __forceinline__ float max3f(float a, float b, float c) { float r; asm("v_max3_f32 %0, %1, %2, %3" : "=v"(r) : "v"(a), "v"(b), "v"(c)); return r; }
; template <int DQK, int DV, bool BIAS> ...
;     ...
;     for (int g = 0; g < NG; ++g) {
;         const int pair = g & 1;
;         __syncthreads();
;         if (g + 1 < NG) {
; #pragma unroll
;             for (int j = 0; j < TPB; ++j) ATT_STORE((pair ^ 1) * TPB + j, j);
;             if (g + 2 < NG) {
; #pragma unroll
;                 for (int j = 0; j < TPB; ++j) ATT_LOAD((g + 2) * TPB + j, j);
;             }
;         }
; #pragma unroll
;       for (int sub = 0; sub < TPB; ++sub) {
;         const int t = g * TPB + sub, buf = pair * TPB + sub, vcur = buf;
;         f32x16 p0, p1;
;         const LAS unsigned char* kb = lds + buf * KBUF + r32 * KP + hi * 16;
; #pragma unroll
;         for (int ks = 0; ks < NKS; ++ks) {
;             const bf16x8 k0 = *(const LAS bf16x8*)(kb + ks * 32), k1 = *(const LAS bf16x8*)(kb + 32 * KP + ks * 32);
;             if (ks == 0) { p0 = __builtin_amdgcn_mfma_f32_32x32x16_bf16(k0, qf[0], negm, 0, 0, 0); p1 = __builtin_amdgcn_mfma_f32_32x32x16_bf16(k1, qf[0], negm, 0, 0, 0); }
;             else { p0 = __builtin_amdgcn_mfma_f32_32x32x16_bf16(k0, qf[ks], p0, 0, 0, 0); p1 = __builtin_amdgcn_mfma_f32_32x32x16_bf16(k1, qf[ks], p1, 0, 0, 0); }
;         }
;         if (BIAS) {
;             asm volatile("s_nop 15\n\ts_nop 7" : "+v"(p0), "+v"(p1));
;             const float d0 = qp - (float)(t * 64 + 4 * hi);
; #pragma unroll
;             for (int r = 0; r < 16; ++r) { const float dk = d0 - (float)((r & 3) + 8 * (r >> 2)); p0[r] = p0[r] - sl2 * fabsf(dk); p1[r] = p1[r] - sl2 * fabsf(dk - 32.f); }
;         } else {
;             asm volatile("s_nop 15\n\ts_nop 7" : "+v"(p0), "+v"(p1));
;         }
;         float mxa = max3f(p0[0], p0[1], p1[0]), mxb = max3f(p0[2], p0[3], p1[1]); mxa = max3f(mxa, p1[2], p1[3]);
; #pragma unroll
;         for (int r = 4; r < 16; r += 4) { mxa = max3f(mxa, p0[r], p0[r + 1]); mxb = max3f(mxb, p0[r + 2], p0[r + 3]); mxa = max3f(mxa, p1[r], p1[r + 1]); mxb = max3f(mxb, p1[r + 2], p1[r + 3]); }
;         float mx = fmaxf(mxa, mxb);
;         if (__any(mx > 8.f)) {
.LBB0_588:
	s_cmp_lt_u32 s7, 62
	s_cselect_b64 s[42:43], -1, 0
	s_cmp_gt_u32 s7, 61
	s_waitcnt lgkmcnt(0)
	s_barrier
	s_waitcnt vmcnt(0)
	ds_write_b128 v174, v[138:141] offset:9216
	ds_write_b128 v175, v[130:133] offset:34816
	ds_write_b128 v175, v[134:137] offset:43008
	s_cbranch_scc1 .LBB0_590
	s_add_u32 s100, s4, 0xca000
	s_addc_u32 s101, s5, 0
	s_add_u32 s100, s100, s16
	s_addc_u32 s101, s101, s17
	global_load_dwordx4 v[130:133], v230, s[100:101] offset:2048
	global_load_dwordx4 v[134:137], v231, s[100:101] offset:2048
	s_add_u32 s100, s100, s98
	s_addc_u32 s101, s101, s99
	global_load_dwordx4 v[138:141], v232, s[100:101] offset:1152
.LBB0_590:
	ds_read_b128 v[82:85], v179
	ds_read_b128 v[152:155], v179 offset:32
	ds_read_b128 v[156:159], v179 offset:4608
	ds_read_b128 v[160:163], v179 offset:4640
	v_cvt_f32_u32_e32 v150, v177
	s_waitcnt lgkmcnt(3)
	v_mfma_f32_32x32x16_bf16 v[98:113], v[82:85], v[114:117], v[66:81]
	v_sub_f32_e32 v182, v176, v150
	v_add_f32_e32 v183, -1.0, v182
	s_waitcnt lgkmcnt(1)
	v_mfma_f32_32x32x16_bf16 v[82:97], v[156:159], v[114:117], v[66:81]
	v_mfma_f32_32x32x16_bf16 v[98:113], v[152:155], v[118:121], v[98:113]
	ds_read_b128 v[152:155], v179 offset:64
	ds_read_b128 v[156:159], v179 offset:96
	s_waitcnt lgkmcnt(2)
	v_mfma_f32_32x32x16_bf16 v[82:97], v[160:163], v[118:121], v[82:97]
	s_waitcnt lgkmcnt(1)
	v_mfma_f32_32x32x16_bf16 v[98:113], v[152:155], v[122:125], v[98:113]
	ds_read_b128 v[152:155], v179 offset:4672
	ds_read_b128 v[160:163], v179 offset:4704
	s_waitcnt lgkmcnt(1)
	v_mfma_f32_32x32x16_bf16 v[82:97], v[152:155], v[122:125], v[82:97]
	v_mfma_f32_32x32x16_bf16 v[98:113], v[156:159], v[126:129], v[98:113]
	s_waitcnt lgkmcnt(0)
	v_mfma_f32_32x32x16_bf16 v[82:97], v[160:163], v[126:129], v[82:97]
	s_nop 15
	s_nop 7
	s_nop 9
	v_fma_f32 v156, -v142, |v182|, v98
	v_fma_f32 v157, -v143, |v183|, v99
	v_pk_add_f32 v[98:99], v[182:183], s[6:7] op_sel_hi:[1,0]
	s_nop 0
	v_fma_f32 v99, -v143, |v99|, v83
	v_fma_f32 v98, -v142, |v98|, v82
	v_pk_add_f32 v[82:83], v[182:183], s[8:9] op_sel_hi:[0,1]
	v_fma_f32 v161, -v143, |v83|, v101
	v_fma_f32 v160, -v142, |v82|, v100
	v_pk_add_f32 v[82:83], v[82:83], s[6:7] op_sel_hi:[1,0]
	v_fma_f32 v153, -v143, |v83|, v85
	v_fma_f32 v152, -v142, |v82|, v84
	v_pk_add_f32 v[82:83], v[182:183], s[10:11] op_sel_hi:[0,1]
	v_fma_f32 v165, -v143, |v83|, v103
	v_fma_f32 v164, -v142, |v82|, v102
	v_pk_add_f32 v[82:83], v[82:83], s[6:7] op_sel_hi:[1,0]
	v_fma_f32 v103, -v143, |v83|, v87
	v_fma_f32 v102, -v142, |v82|, v86
	v_pk_add_f32 v[82:83], v[182:183], s[22:23] op_sel_hi:[0,1]
	v_fma_f32 v167, -v143, |v83|, v105
	v_fma_f32 v166, -v142, |v82|, v104
	v_pk_add_f32 v[82:83], v[82:83], s[6:7] op_sel_hi:[1,0]
	v_fma_f32 v155, -v143, |v83|, v89
	v_fma_f32 v154, -v142, |v82|, v88
	v_pk_add_f32 v[82:83], v[182:183], s[34:35] op_sel_hi:[0,1]
	v_fma_f32 v159, -v143, |v83|, v107
	v_fma_f32 v158, -v142, |v82|, v106
	v_pk_add_f32 v[82:83], v[82:83], s[6:7] op_sel_hi:[1,0]
	v_fma_f32 v101, -v143, |v83|, v91
	v_fma_f32 v100, -v142, |v82|, v90
	v_pk_add_f32 v[82:83], v[182:183], s[36:37] op_sel_hi:[0,1]
	v_fma_f32 v163, -v143, |v83|, v109
	v_fma_f32 v162, -v142, |v82|, v108
	v_pk_add_f32 v[82:83], v[82:83], s[6:7] op_sel_hi:[1,0]
	v_fma_f32 v105, -v143, |v83|, v93
	v_fma_f32 v104, -v142, |v82|, v92
	v_pk_add_f32 v[82:83], v[182:183], s[38:39] op_sel_hi:[0,1]
	v_fma_f32 v111, -v143, |v83|, v111
	v_fma_f32 v110, -v142, |v82|, v110
	v_pk_add_f32 v[82:83], v[82:83], s[6:7] op_sel_hi:[1,0]
	v_fma_f32 v107, -v143, |v83|, v95
	v_fma_f32 v106, -v142, |v82|, v94
	v_pk_add_f32 v[82:83], v[182:183], s[40:41] op_sel_hi:[0,1]
	v_fma_f32 v113, -v143, |v83|, v113
	v_fma_f32 v112, -v142, |v82|, v112
	v_pk_add_f32 v[82:83], v[82:83], s[6:7] op_sel_hi:[1,0]
	v_fma_f32 v109, -v143, |v83|, v97
	v_fma_f32 v108, -v142, |v82|, v96
	v_max3_f32 v82, v156, v157, v98
	v_max3_f32 v83, v160, v161, v99
	v_max3_f32 v82, v82, v152, v153
	v_max3_f32 v83, v83, v166, v167
	v_max3_f32 v82, v82, v164, v165
	v_max3_f32 v83, v83, v154, v155
	v_max3_f32 v82, v82, v102, v103
	v_max3_f32 v83, v83, v162, v163
	v_max3_f32 v82, v82, v158, v159
	v_max3_f32 v83, v83, v104, v105
	v_max3_f32 v82, v82, v100, v101
	v_max3_f32 v83, v83, v112, v113
	v_max3_f32 v82, v82, v110, v111
	v_max3_f32 v83, v83, v108, v109
	v_max3_f32 v82, v82, v106, v107
	v_max_f32_e32 v82, v82, v83
	v_cmp_gt_f32_e32 vcc, 0xc3400000, v82
	s_cmp_eq_u64 vcc, exec
	s_cbranch_scc1 .Lsk1_p4a2
; template <int DQK, int DV, bool BIAS> ...
;     ...
;         if (__any(mx > 8.f)) {
;             mx = fmaxf(mx, __shfl_xor(mx, 32));
;             const float dl = fmaxf(mx, 0.f); mhat += dl;
;             const float f = __builtin_amdgcn_exp2f(-dl);
; #pragma unroll
;             for (int r = 0; r < 16; ++r) { p0[r] -= dl; p1[r] -= dl; negm[r] = -mhat; }
;             l *= f;
; #pragma unroll
;             for (int d = 0; d < NDT; ++d)
; #pragma unroll
;                 for (int r = 0; r < 16; ++r) o[d][r] *= f;
;         }
	v_cmp_lt_f32_e32 vcc, s44, v82
	s_cbranch_vccz .LBB0_592
	ds_bpermute_b32 v66, v168, v82
	s_waitcnt lgkmcnt(0)
	v_max3_f32 v67, v82, v66, 0
	v_exp_f32_e64 v66, -v67
	v_add_f32_e32 v180, v180, v67
	v_xor_b32_e32 v82, 0x80000000, v180
	v_sub_f32_e32 v98, v98, v67
	v_sub_f32_e32 v99, v99, v67
	v_sub_f32_e32 v152, v152, v67
	v_sub_f32_e32 v153, v153, v67
	v_sub_f32_e32 v102, v102, v67
	v_sub_f32_e32 v103, v103, v67
	v_sub_f32_e32 v154, v154, v67
	v_sub_f32_e32 v155, v155, v67
	v_sub_f32_e32 v100, v100, v67
	v_sub_f32_e32 v101, v101, v67
	v_sub_f32_e32 v104, v104, v67
	v_sub_f32_e32 v105, v105, v67
	v_sub_f32_e32 v106, v106, v67
	v_sub_f32_e32 v107, v107, v67
	v_sub_f32_e32 v108, v108, v67
	v_sub_f32_e32 v109, v109, v67
	v_pk_mul_f32 v[16:17], v[16:17], v[66:67] op_sel_hi:[1,0]
	v_pk_mul_f32 v[14:15], v[14:15], v[66:67] op_sel_hi:[1,0]
	v_pk_mul_f32 v[12:13], v[12:13], v[66:67] op_sel_hi:[1,0]
	v_pk_mul_f32 v[10:11], v[10:11], v[66:67] op_sel_hi:[1,0]
	v_pk_mul_f32 v[8:9], v[8:9], v[66:67] op_sel_hi:[1,0]
	v_pk_mul_f32 v[6:7], v[6:7], v[66:67] op_sel_hi:[1,0]
	v_pk_mul_f32 v[4:5], v[4:5], v[66:67] op_sel_hi:[1,0]
	v_pk_mul_f32 v[2:3], v[2:3], v[66:67] op_sel_hi:[1,0]
	v_pk_mul_f32 v[32:33], v[32:33], v[66:67] op_sel_hi:[1,0]
	v_pk_mul_f32 v[30:31], v[30:31], v[66:67] op_sel_hi:[1,0]
	v_pk_mul_f32 v[28:29], v[28:29], v[66:67] op_sel_hi:[1,0]
	v_pk_mul_f32 v[26:27], v[26:27], v[66:67] op_sel_hi:[1,0]
	v_pk_mul_f32 v[24:25], v[24:25], v[66:67] op_sel_hi:[1,0]
	v_pk_mul_f32 v[22:23], v[22:23], v[66:67] op_sel_hi:[1,0]
	v_pk_mul_f32 v[20:21], v[20:21], v[66:67] op_sel_hi:[1,0]
	v_pk_mul_f32 v[18:19], v[18:19], v[66:67] op_sel_hi:[1,0]
	v_pk_mul_f32 v[48:49], v[48:49], v[66:67] op_sel_hi:[1,0]
	v_pk_mul_f32 v[46:47], v[46:47], v[66:67] op_sel_hi:[1,0]
	v_pk_mul_f32 v[44:45], v[44:45], v[66:67] op_sel_hi:[1,0]
	v_pk_mul_f32 v[42:43], v[42:43], v[66:67] op_sel_hi:[1,0]
	v_pk_mul_f32 v[40:41], v[40:41], v[66:67] op_sel_hi:[1,0]
	v_pk_mul_f32 v[38:39], v[38:39], v[66:67] op_sel_hi:[1,0]
	v_pk_mul_f32 v[36:37], v[36:37], v[66:67] op_sel_hi:[1,0]
	v_pk_mul_f32 v[34:35], v[34:35], v[66:67] op_sel_hi:[1,0]
	v_pk_mul_f32 v[64:65], v[64:65], v[66:67] op_sel_hi:[1,0]
	v_pk_mul_f32 v[62:63], v[62:63], v[66:67] op_sel_hi:[1,0]
	v_pk_mul_f32 v[60:61], v[60:61], v[66:67] op_sel_hi:[1,0]
	v_pk_mul_f32 v[58:59], v[58:59], v[66:67] op_sel_hi:[1,0]
	v_pk_mul_f32 v[56:57], v[56:57], v[66:67] op_sel_hi:[1,0]
	v_pk_mul_f32 v[54:55], v[54:55], v[66:67] op_sel_hi:[1,0]
	v_pk_mul_f32 v[52:53], v[52:53], v[66:67] op_sel_hi:[1,0]
	v_pk_mul_f32 v[50:51], v[50:51], v[66:67] op_sel_hi:[1,0]
	v_sub_f32_e32 v156, v156, v67
	v_sub_f32_e32 v157, v157, v67
	v_sub_f32_e32 v160, v160, v67
	v_sub_f32_e32 v161, v161, v67
	v_sub_f32_e32 v164, v164, v67
	v_sub_f32_e32 v165, v165, v67
	v_sub_f32_e32 v166, v166, v67
	v_sub_f32_e32 v167, v167, v67
	v_sub_f32_e32 v158, v158, v67
	v_sub_f32_e32 v159, v159, v67
	v_sub_f32_e32 v162, v162, v67
	v_sub_f32_e32 v163, v163, v67
	v_sub_f32_e32 v110, v110, v67
	v_sub_f32_e32 v111, v111, v67
	v_sub_f32_e32 v112, v112, v67
	v_sub_f32_e32 v113, v113, v67
	v_mul_f32_e32 v151, v151, v66
	v_mov_b32_e32 v66, v82
	v_mov_b32_e32 v67, v82
	v_mov_b32_e32 v68, v82
	v_mov_b32_e32 v69, v82
	v_mov_b32_e32 v70, v82
	v_mov_b32_e32 v71, v82
	v_mov_b32_e32 v72, v82
	v_mov_b32_e32 v73, v82
	v_mov_b32_e32 v74, v82
	v_mov_b32_e32 v75, v82
	v_mov_b32_e32 v76, v82
	v_mov_b32_e32 v77, v82
	v_mov_b32_e32 v78, v82
	v_mov_b32_e32 v79, v82
	v_mov_b32_e32 v80, v82
	v_mov_b32_e32 v81, v82
	s_branch .LBB0_593

; #define LAS __attribute__((address_space(3)))
; template <int DQK, int DV, bool BIAS> ...
;     ...
;     for (int g = 0; g < NG; ++g) {
;         const int pair = g & 1;
;         __syncthreads();
;         if (g + 1 < NG) {
; #pragma unroll
;             for (int j = 0; j < TPB; ++j) ATT_STORE((pair ^ 1) * TPB + j, j);
;             if (g + 2 < NG) {
; #pragma unroll
;                 for (int j = 0; j < TPB; ++j) ATT_LOAD((g + 2) * TPB + j, j);
;             }
;         }
; #pragma unroll
;       for (int sub = 0; sub < TPB; ++sub) {
;         const int t = g * TPB + sub, buf = pair * TPB + sub, vcur = buf;
;         f32x16 p0, p1;
;         const LAS unsigned char* kb = lds + buf * KBUF + r32 * KP + hi * 16;
; #pragma unroll
;         for (int ks = 0; ks < NKS; ++ks) {
;             const bf16x8 k0 = *(const LAS bf16x8*)(kb + ks * 32), k1 = *(const LAS bf16x8*)(kb + 32 * KP + ks * 32);
;             if (ks == 0) { p0 = __builtin_amdgcn_mfma_f32_32x32x16_bf16(k0, qf[0], negm, 0, 0, 0); p1 = __builtin_amdgcn_mfma_f32_32x32x16_bf16(k1, qf[0], negm, 0, 0, 0); }
;             else { p0 = __builtin_amdgcn_mfma_f32_32x32x16_bf16(k0, qf[ks], p0, 0, 0, 0); p1 = __builtin_amdgcn_mfma_f32_32x32x16_bf16(k1, qf[ks], p1, 0, 0, 0); }
;         }
;         if (BIAS) {
;             asm volatile("s_nop 15\n\ts_nop 7" : "+v"(p0), "+v"(p1));
;             const float d0 = qp - (float)(t * 64 + 4 * hi);
; #pragma unroll
;             for (int r = 0; r < 16; ++r) { const float dk = d0 - (float)((r & 3) + 8 * (r >> 2)); p0[r] = p0[r] - sl2 * fabsf(dk); p1[r] = p1[r] - sl2 * fabsf(dk - 32.f); }
;         } else {
;             asm volatile("s_nop 15\n\ts_nop 7" : "+v"(p0), "+v"(p1));
;         }
;         float mxa = max3f(p0[0], p0[1], p1[0]), mxb = max3f(p0[2], p0[3], p1[1]); mxa = max3f(mxa, p1[2], p1[3]);
; #pragma unroll
;         for (int r = 4; r < 16; r += 4) { mxa = max3f(mxa, p0[r], p0[r + 1]); mxb = max3f(mxb, p0[r + 2], p0[r + 3]); mxa = max3f(mxa, p1[r], p1[r + 1]); mxb = max3f(mxb, p1[r + 2], p1[r + 3]); }
;         float mx = fmaxf(mxa, mxb);
;         if (__any(mx > 8.f)) {
;     ...
;             float ls = 0.f;
; #pragma unroll
;             for (int hs = 0; hs < 4; ++hs) {
;                 float e[8];
; #pragma unroll
;                 for (int j = 0; j < 8; ++j) { e[j] = __builtin_amdgcn_exp2f(hs < 2 ? p0[8 * (hs & 1) + j] : p1[8 * (hs & 1) + j]); ls += e[j]; }
.Lend1_p4a2:
	s_cmp_eq_u32 s4, 0x1876000
	s_barrier
	s_cbranch_scc1 .LBB0_596
	s_andn2_b64 vcc, exec, s[42:43]
	s_waitcnt vmcnt(0)
	ds_write_b128 v174, v[138:141]
	ds_write_b128 v175, v[130:133] offset:18432
	ds_write_b128 v175, v[134:137] offset:26624
	s_cbranch_vccnz .LBB0_596
	s_add_u32 s100, s4, 0x12f000
	s_addc_u32 s101, s5, 0
	s_add_u32 s100, s100, s16
	s_addc_u32 s101, s101, s17
	global_load_dwordx4 v[130:133], v230, s[100:101] offset:2048
	global_load_dwordx4 v[134:137], v231, s[100:101] offset:2048
	s_add_u32 s100, s100, s98
	s_addc_u32 s101, s101, s99
	global_load_dwordx4 v[138:141], v232, s[100:101] offset:1152
.LBB0_596:
	ds_read_b128 v[196:199], v179 offset:9216
	ds_read_b128 v[200:203], v179 offset:9248
	v_add_f32_e32 v156, v157, v156
	v_add_f32_e32 v156, v160, v156
	s_waitcnt lgkmcnt(1)
	v_mfma_f32_32x32x16_bf16 v[98:113], v[196:199], v[114:117], v[66:81]
	ds_read_b128 v[196:199], v179 offset:13824
	ds_read_b128 v[204:207], v179 offset:13856
	v_add_f32_e32 v156, v161, v156
	v_add_f32_e32 v156, v164, v156
	v_add_f32_e32 v150, v150, v156
	v_add_f32_e32 v150, v165, v150
	v_add_f32_e32 v150, v166, v150
	v_add_f32_e32 v150, v167, v150
	s_waitcnt lgkmcnt(1)
	v_mfma_f32_32x32x16_bf16 v[82:97], v[196:199], v[114:117], v[66:81]
	v_add_f32_e32 v150, v181, v150
	v_add_f32_e32 v150, v182, v150
	v_add_f32_e32 v150, v158, v150
	v_add_f32_e32 v150, v159, v150
	ds_read_b128 v[164:167], v179 offset:9280
	v_add_f32_e32 v150, v162, v150
	v_add_f32_e32 v150, v163, v150
	v_mfma_f32_32x32x16_bf16 v[98:113], v[200:203], v[118:121], v[98:113]
	v_add_f32_e32 v150, v183, v150
	v_add_f32_e32 v150, v184, v150
	v_add_f32_e32 v150, v185, v150
	v_add_f32_e32 v150, v152, v150
	ds_read_b128 v[156:159], v179 offset:13888
	ds_read_b128 v[160:163], v179 offset:9312
	v_add_f32_e32 v150, v153, v150
	v_add_f32_e32 v150, v186, v150
	s_waitcnt lgkmcnt(3)
	v_mfma_f32_32x32x16_bf16 v[82:97], v[204:207], v[118:121], v[82:97]
	v_add_f32_e32 v150, v187, v150
	v_add_f32_e32 v150, v154, v150
	v_add_f32_e32 v150, v155, v150
	v_add_f32_e32 v150, v188, v150
	v_add_f32_e32 v150, v189, v150
	v_add_u32_e32 v152, 64, v177
	v_add_f32_e32 v150, v190, v150
	s_waitcnt lgkmcnt(2)
	v_mfma_f32_32x32x16_bf16 v[98:113], v[164:167], v[122:125], v[98:113]
	ds_read_b128 v[164:167], v179 offset:13920
	v_cvt_f32_u32_e32 v152, v152
	v_add_f32_e32 v150, v191, v150
	v_add_f32_e32 v150, v192, v150
	v_add_f32_e32 v150, v195, v150
	v_add_f32_e32 v150, v193, v150
	v_add_f32_e32 v150, v194, v150
	s_waitcnt lgkmcnt(2)
	v_mfma_f32_32x32x16_bf16 v[82:97], v[156:159], v[122:125], v[82:97]
	v_add_f32_e32 v158, v151, v150
	s_waitcnt lgkmcnt(1)
	v_mfma_f32_32x32x16_bf16 v[98:113], v[160:163], v[126:129], v[98:113]
	v_sub_f32_e32 v160, v176, v152
	v_add_f32_e32 v161, -1.0, v160
	s_waitcnt lgkmcnt(0)
	v_mfma_f32_32x32x16_bf16 v[82:97], v[164:167], v[126:129], v[82:97]
	s_nop 15
	s_nop 7
	s_nop 5
	v_fma_f32 v150, -v142, |v160|, v98
	v_fma_f32 v151, -v143, |v161|, v99
	v_pk_add_f32 v[98:99], v[160:161], s[6:7] op_sel_hi:[1,0]
	s_nop 0
	v_fma_f32 v83, -v143, |v99|, v83
	v_fma_f32 v82, -v142, |v98|, v82
	s_nop 0
	v_pk_add_f32 v[98:99], v[160:161], s[8:9] op_sel_hi:[0,1]
	v_fma_f32 v153, -v143, |v99|, v101
	v_fma_f32 v152, -v142, |v98|, v100
	v_pk_add_f32 v[98:99], v[98:99], s[6:7] op_sel_hi:[1,0]
	v_fma_f32 v99, -v143, |v99|, v85
	v_fma_f32 v98, -v142, |v98|, v84
	v_pk_add_f32 v[84:85], v[160:161], s[10:11] op_sel_hi:[0,1]
	v_fma_f32 v155, -v143, |v85|, v103
	v_fma_f32 v154, -v142, |v84|, v102
	v_pk_add_f32 v[84:85], v[84:85], s[6:7] op_sel_hi:[1,0]
	v_fma_f32 v101, -v143, |v85|, v87
	v_fma_f32 v100, -v142, |v84|, v86
	v_pk_add_f32 v[84:85], v[160:161], s[22:23] op_sel_hi:[0,1]
	v_fma_f32 v157, -v143, |v85|, v105
	v_fma_f32 v156, -v142, |v84|, v104
	v_pk_add_f32 v[84:85], v[84:85], s[6:7] op_sel_hi:[1,0]
	v_fma_f32 v103, -v143, |v85|, v89
	v_fma_f32 v102, -v142, |v84|, v88
	v_pk_add_f32 v[84:85], v[160:161], s[34:35] op_sel_hi:[0,1]
	v_fma_f32 v105, -v143, |v85|, v107
	v_fma_f32 v104, -v142, |v84|, v106
	v_pk_add_f32 v[86:87], v[160:161], s[36:37] op_sel_hi:[0,1]
	v_pk_add_f32 v[84:85], v[84:85], s[6:7] op_sel_hi:[1,0]
	v_fma_f32 v107, -v143, |v87|, v109
	v_fma_f32 v106, -v142, |v86|, v108
	v_fma_f32 v85, -v143, |v85|, v91
	v_fma_f32 v84, -v142, |v84|, v90
	v_pk_add_f32 v[86:87], v[86:87], s[6:7] op_sel_hi:[1,0]
	v_pk_add_f32 v[88:89], v[160:161], s[38:39] op_sel_hi:[0,1]
	v_fma_f32 v87, -v143, |v87|, v93
	v_fma_f32 v86, -v142, |v86|, v92
	v_fma_f32 v93, -v143, |v89|, v111
	v_fma_f32 v92, -v142, |v88|, v110
	v_pk_add_f32 v[88:89], v[88:89], s[6:7] op_sel_hi:[1,0]
	v_fma_f32 v89, -v143, |v89|, v95
	v_fma_f32 v88, -v142, |v88|, v94
	v_pk_add_f32 v[90:91], v[160:161], s[40:41] op_sel_hi:[0,1]
	v_fma_f32 v95, -v143, |v91|, v113
	v_fma_f32 v94, -v142, |v90|, v112
	v_pk_add_f32 v[90:91], v[90:91], s[6:7] op_sel_hi:[1,0]
	v_fma_f32 v91, -v143, |v91|, v97
	v_fma_f32 v90, -v142, |v90|, v96
	v_max3_f32 v96, v150, v151, v82
	v_max3_f32 v97, v152, v153, v83
	v_max3_f32 v96, v96, v98, v99
	v_max3_f32 v97, v97, v156, v157
	v_max3_f32 v96, v96, v154, v155
	v_max3_f32 v97, v97, v102, v103
	v_max3_f32 v96, v96, v100, v101
	v_max3_f32 v97, v97, v106, v107
	v_max3_f32 v96, v96, v104, v105
	v_max3_f32 v97, v97, v86, v87
	v_max3_f32 v96, v96, v84, v85
	v_max3_f32 v97, v97, v94, v95
	v_max3_f32 v96, v96, v92, v93
	v_max3_f32 v97, v97, v90, v91
	v_max3_f32 v96, v96, v88, v89
	v_max_f32_e32 v96, v96, v97
	v_cmp_gt_f32_e32 vcc, 0xc3400000, v96
	s_cmp_eq_u64 vcc, exec
	s_cbranch_scc1 .Lsk2_p4a2
; template <int DQK, int DV, bool BIAS> ...
;     ...
;         if (__any(mx > 8.f)) {
;             mx = fmaxf(mx, __shfl_xor(mx, 32));
;             const float dl = fmaxf(mx, 0.f); mhat += dl;
;             const float f = __builtin_amdgcn_exp2f(-dl);
; #pragma unroll
;             for (int r = 0; r < 16; ++r) { p0[r] -= dl; p1[r] -= dl; negm[r] = -mhat; }
;             l *= f;
; #pragma unroll
;             for (int d = 0; d < NDT; ++d)
; #pragma unroll
;                 for (int r = 0; r < 16; ++r) o[d][r] *= f;
;         }
	v_cmp_lt_f32_e32 vcc, s44, v96
	s_cbranch_vccz .LBB0_587
	ds_bpermute_b32 v66, v168, v96
	s_waitcnt lgkmcnt(0)
	v_max3_f32 v67, v96, v66, 0
	v_exp_f32_e64 v68, -v67
	v_add_f32_e32 v180, v180, v67
	v_xor_b32_e32 v66, 0x80000000, v180
	v_sub_f32_e32 v82, v82, v67
	v_sub_f32_e32 v83, v83, v67
	v_sub_f32_e32 v98, v98, v67
	v_sub_f32_e32 v99, v99, v67
	v_sub_f32_e32 v100, v100, v67
	v_sub_f32_e32 v101, v101, v67
	v_sub_f32_e32 v102, v102, v67
	v_sub_f32_e32 v103, v103, v67
	v_sub_f32_e32 v84, v84, v67
	v_sub_f32_e32 v85, v85, v67
	v_sub_f32_e32 v86, v86, v67
	v_sub_f32_e32 v87, v87, v67
	v_sub_f32_e32 v88, v88, v67
	v_sub_f32_e32 v89, v89, v67
	v_sub_f32_e32 v90, v90, v67
	v_sub_f32_e32 v91, v91, v67
	v_pk_mul_f32 v[16:17], v[16:17], v[68:69] op_sel_hi:[1,0]
	v_pk_mul_f32 v[14:15], v[14:15], v[68:69] op_sel_hi:[1,0]
	v_pk_mul_f32 v[12:13], v[12:13], v[68:69] op_sel_hi:[1,0]
	v_pk_mul_f32 v[10:11], v[10:11], v[68:69] op_sel_hi:[1,0]
	v_pk_mul_f32 v[8:9], v[8:9], v[68:69] op_sel_hi:[1,0]
	v_pk_mul_f32 v[6:7], v[6:7], v[68:69] op_sel_hi:[1,0]
	v_pk_mul_f32 v[4:5], v[4:5], v[68:69] op_sel_hi:[1,0]
	v_pk_mul_f32 v[2:3], v[2:3], v[68:69] op_sel_hi:[1,0]
	v_pk_mul_f32 v[32:33], v[32:33], v[68:69] op_sel_hi:[1,0]
	v_pk_mul_f32 v[30:31], v[30:31], v[68:69] op_sel_hi:[1,0]
	v_pk_mul_f32 v[28:29], v[28:29], v[68:69] op_sel_hi:[1,0]
	v_pk_mul_f32 v[26:27], v[26:27], v[68:69] op_sel_hi:[1,0]
	v_pk_mul_f32 v[24:25], v[24:25], v[68:69] op_sel_hi:[1,0]
	v_pk_mul_f32 v[22:23], v[22:23], v[68:69] op_sel_hi:[1,0]
	v_pk_mul_f32 v[20:21], v[20:21], v[68:69] op_sel_hi:[1,0]
	v_pk_mul_f32 v[18:19], v[18:19], v[68:69] op_sel_hi:[1,0]
	v_pk_mul_f32 v[48:49], v[48:49], v[68:69] op_sel_hi:[1,0]
	v_pk_mul_f32 v[46:47], v[46:47], v[68:69] op_sel_hi:[1,0]
	v_pk_mul_f32 v[44:45], v[44:45], v[68:69] op_sel_hi:[1,0]
	v_pk_mul_f32 v[42:43], v[42:43], v[68:69] op_sel_hi:[1,0]
	v_pk_mul_f32 v[40:41], v[40:41], v[68:69] op_sel_hi:[1,0]
	v_pk_mul_f32 v[38:39], v[38:39], v[68:69] op_sel_hi:[1,0]
	v_pk_mul_f32 v[36:37], v[36:37], v[68:69] op_sel_hi:[1,0]
	v_pk_mul_f32 v[34:35], v[34:35], v[68:69] op_sel_hi:[1,0]
	v_pk_mul_f32 v[64:65], v[64:65], v[68:69] op_sel_hi:[1,0]
	v_pk_mul_f32 v[62:63], v[62:63], v[68:69] op_sel_hi:[1,0]
	v_pk_mul_f32 v[60:61], v[60:61], v[68:69] op_sel_hi:[1,0]
	v_pk_mul_f32 v[58:59], v[58:59], v[68:69] op_sel_hi:[1,0]
	v_pk_mul_f32 v[56:57], v[56:57], v[68:69] op_sel_hi:[1,0]
	v_pk_mul_f32 v[54:55], v[54:55], v[68:69] op_sel_hi:[1,0]
	v_pk_mul_f32 v[52:53], v[52:53], v[68:69] op_sel_hi:[1,0]
	v_pk_mul_f32 v[50:51], v[50:51], v[68:69] op_sel_hi:[1,0]
	v_sub_f32_e32 v150, v150, v67
	v_sub_f32_e32 v151, v151, v67
	v_sub_f32_e32 v152, v152, v67
	v_sub_f32_e32 v153, v153, v67
	v_sub_f32_e32 v154, v154, v67
	v_sub_f32_e32 v155, v155, v67
	v_sub_f32_e32 v156, v156, v67
	v_sub_f32_e32 v157, v157, v67
	v_sub_f32_e32 v104, v104, v67
	v_sub_f32_e32 v105, v105, v67
	v_sub_f32_e32 v106, v106, v67
	v_sub_f32_e32 v107, v107, v67
	v_sub_f32_e32 v92, v92, v67
	v_sub_f32_e32 v93, v93, v67
	v_sub_f32_e32 v94, v94, v67
	v_sub_f32_e32 v95, v95, v67
	v_mul_f32_e32 v158, v158, v68
	v_mov_b32_e32 v67, v66
	v_mov_b32_e32 v68, v66
	v_mov_b32_e32 v69, v66
	v_mov_b32_e32 v70, v66
	v_mov_b32_e32 v71, v66
	v_mov_b32_e32 v72, v66
	v_mov_b32_e32 v73, v66
	v_mov_b32_e32 v74, v66
	v_mov_b32_e32 v75, v66
	v_mov_b32_e32 v76, v66
	v_mov_b32_e32 v77, v66
	v_mov_b32_e32 v78, v66
	v_mov_b32_e32 v79, v66
	v_mov_b32_e32 v80, v66
	v_mov_b32_e32 v81, v66
	s_branch .LBB0_587

; template <int DQK, int DV, bool BIAS> ...
;     ...
;     for (int ks = 0; ks < NKS; ++ks) qf[ks] = ks < 4 ? *(const bf16x8*)(Qw + (size_t)r32 * ldq + ks * 16 + hi * 8) : *(const bf16x8*)(Q2w + (size_t)r32 * ldq2 + (ks - 4) * 16 + hi * 8);
; #pragma unroll
;     for (int ks = 0; ks < 4; ++ks) qf[ks] = scale_frag(qf[ks], cs);
;     if constexpr (DQK == 96) {
;         const float* rp = ropetab + ((size_t)(qpos0 + r32) * 16) * 2;
; #pragma unroll
;         for (int ks = 4; ks < 6; ++ks) {
;             const f32x4 c0 = *(const f32x4*)(rp + ((ks - 4) * 8 + hi * 4) * 2), c1 = *(const f32x4*)(rp + ((ks - 4) * 8 + hi * 4 + 2) * 2);
;             const u32x4 w = __builtin_bit_cast(u32x4, qf[ks]); u32x4 ow;
;             { const float a = bflo(w.x) * cs, b = bfhi(w.x) * cs; ow.x = cvtpk(a * c0[0] - b * c0[1], a * c0[1] + b * c0[0]); }
;             { const float a = bflo(w.y) * cs, b = bfhi(w.y) * cs; ow.y = cvtpk(a * c0[2] - b * c0[3], a * c0[3] + b * c0[2]); }
;             { const float a = bflo(w.z) * cs, b = bfhi(w.z) * cs; ow.z = cvtpk(a * c1[0] - b * c1[1], a * c1[1] + b * c1[0]); }
;             { const float a = bflo(w.w) * cs, b = bfhi(w.w) * cs; ow.w = cvtpk(a * c1[2] - b * c1[3], a * c1[3] + b * c1[2]); }
;             qf[ks] = __builtin_bit_cast(bf16x8, ow);
;         }
;     }
; #pragma unroll
;     for (int d = 0; d < NDT; ++d)
; #pragma unroll
;         for (int r = 0; r < 16; ++r) o[d][r] = 0.f;
; #pragma unroll
;     for (int ks = 0; ks < NKS; ++ks) asm volatile("" : "+v"(qf[ks]));
;     float mhat = 0.f, l = 0.f; f32x16 negm;
; __device__ __forceinline__ void attn_phase(PPtr P, int li, LAS unsigned char* lds, int vcu, int wave, int lane) {
;     bf16_t* proj = (bf16_t*)(P->ws + OFF_PROJ); bf16_t* mlaq = (bf16_t*)(P->ws + OFF_MLAQ); const bf16_t* mlakv = (const bf16_t*)(P->ws + OFF_MLAKV);
;     const int r32 = lane & 31, hi = lane >> 5;
;     {
;         const int b = vcu >> 6, h = (vcu >> 4) & 3, qb = vcu & 15;
;         const size_t seq0 = (size_t)b * SEQL, qrow = seq0 + qb * 256 + wave * 32;
;         const float slope = __builtin_amdgcn_exp2f(-2.f * (float)(h + 1));
;         f32x16 o1[4], o2[4];
;         attn_pass<64, 128, true>(lds, proj + qrow * LDP + C_AQ + h * 128, LDP, nullptr, 0, proj + seq0 * LDP + C_AK + h * 128, LDP, nullptr, 0, proj + seq0 * LDP + C_AV + h * 128, LDP, qb * 256 + wave * 32, 0.125f * LOG2E, slope * LOG2E, nullptr, o1);
.LBB0_2001:
	s_cmp_lt_i32 s24, 15
	s_cselect_b64 s[4:5], -1, 0
	s_cmp_gt_i32 s25, 14
	s_cselect_b64 s[6:7], -1, 0
	s_and_b64 s[4:5], s[4:5], s[6:7]
	s_andn2_b64 vcc, exec, s[4:5]
	s_cbranch_vccnz .LBB0_2179
	s_mov_b64 s[20:21], s[0:1]
	v_mov_b32_e32 v169, v1
	s_load_dwordx2 s[16:17], s[20:21], 0x118
	s_ashr_i32 s4, s33, 6
	v_readfirstlane_b32 s3, v169
	s_ashr_i32 s50, s3, 6
	s_ashr_i32 s5, s4, 31
	s_lshl_b32 s3, s33, 8
	s_lshl_b64 s[6:7], s[4:5], 12
	s_and_b32 s27, s3, 0xf00
	s_lshl_b32 s46, s50, 5
	s_bfe_u32 s8, s33, 0x20004
	s_or_b32 s3, s6, s27
	s_ashr_i32 s47, s46, 31
	s_add_u32 s5, s3, s46
	s_addc_u32 s6, s7, s47
	s_not_b32 s3, s8
	s_mulk_i32 s6, 0x1940
	s_mul_hi_u32 s7, s5, 0x1940
	s_lshl_b32 s3, s3, 1
	s_add_i32 s7, s7, s6
	s_mulk_i32 s5, 0x1940
	s_waitcnt lgkmcnt(0)
	s_add_u32 s5, s16, s5
	v_mov_b32_e32 v32, v1
	s_addc_u32 s6, s17, s7
	s_lshl_b32 s9, s8, 8
	s_add_u32 s18, s5, s9
	v_and_b32_e32 v33, 31, v32
	v_mul_u32_u24_e32 v2, 0xca0, v33
	s_addc_u32 s19, s6, 0
	v_bfe_u32 v34, v32, 5, 1
	v_lshlrev_b32_e32 v150, 1, v2
	v_mov_b32_e32 v151, 0
	v_lshl_add_u64 v[2:3], s[18:19], 0, v[150:151]
	v_lshlrev_b32_e32 v150, 4, v34
	v_lshl_add_u64 v[18:19], v[2:3], 0, v[150:151]
	global_load_dwordx4 v[2:5], v[18:19], off
	global_load_dwordx4 v[6:9], v[18:19], off offset:32
	global_load_dwordx4 v[10:13], v[18:19], off offset:64
	global_load_dwordx4 v[14:17], v[18:19], off offset:96
	s_movk_i32 s7, 0x1940
	s_mov_b32 s6, 0x3e38aa3b
	s_mul_i32 s49, s4, 0x1940000
	s_mul_hi_i32 s48, s4, 0x1940000
	s_add_u32 s4, s16, s49
	s_addc_u32 s5, s17, s48
	s_add_u32 s4, s4, s9
	s_addc_u32 s5, s5, 0
	s_mov_b32 s8, 0x65000
	v_lshlrev_b32_e32 v173, 2, v34
	s_mov_b32 s22, 0xc1000000
	s_mov_b32 s34, 0xc1200000
	s_mov_b32 s36, 0xc1800000
	s_mov_b32 s38, 0xc1900000
	s_mov_b32 s40, 0xc1c00000
	s_mov_b32 s42, 0xc1d00000
	s_mov_b32 s51, 0
	s_mov_b32 s23, 0xc1100000
	s_mov_b32 s35, 0xc1300000
	s_mov_b32 s37, 0xc1880000
	s_mov_b32 s39, 0xc1980000
	s_mov_b32 s41, 0xc1c80000
	s_mov_b32 s43, 0xc1d80000
	s_mov_b32 s52, 0x41000000
	v_mov_b32_e32 v176, v151
	v_mov_b32_e32 v66, v151
	v_mov_b32_e32 v67, v151
	v_mov_b32_e32 v68, v151
	v_mov_b32_e32 v69, v151
	v_mov_b32_e32 v70, v151
	v_mov_b32_e32 v71, v151
	v_mov_b32_e32 v72, v151
	v_mov_b32_e32 v73, v151
	v_mov_b32_e32 v74, v151
	v_mov_b32_e32 v75, v151
	v_mov_b32_e32 v76, v151
	v_mov_b32_e32 v77, v151
	v_mov_b32_e32 v78, v151
	v_mov_b32_e32 v79, v151
	v_mov_b32_e32 v80, v151
	v_mov_b32_e32 v81, v151
	s_waitcnt vmcnt(0)
; __device__ __forceinline__ unsigned cvtpk(float lo, float hi) { typedef __bf16 bf2 __attribute__((ext_vector_type(2))); f32x2 v = {lo, hi}; bf2 b = __builtin_convertvector(v, bf2); return __builtin_bit_cast(unsigned, b); }
; template <int DQK, int DV, bool BIAS> ...
;     ...
;     for (int ks = 0; ks < NKS; ++ks) qf[ks] = ks < 4 ? *(const bf16x8*)(Qw + (size_t)r32 * ldq + ks * 16 + hi * 8) : *(const bf16x8*)(Q2w + (size_t)r32 * ldq2 + (ks - 4) * 16 + hi * 8);
; #pragma unroll
;     for (int ks = 0; ks < 4; ++ks) qf[ks] = scale_frag(qf[ks], cs);
;     if constexpr (DQK == 96) {
;         const float* rp = ropetab + ((size_t)(qpos0 + r32) * 16) * 2;
; #pragma unroll
;         for (int ks = 4; ks < 6; ++ks) {
;             const f32x4 c0 = *(const f32x4*)(rp + ((ks - 4) * 8 + hi * 4) * 2), c1 = *(const f32x4*)(rp + ((ks - 4) * 8 + hi * 4 + 2) * 2);
;             const u32x4 w = __builtin_bit_cast(u32x4, qf[ks]); u32x4 ow;
;             { const float a = bflo(w.x) * cs, b = bfhi(w.x) * cs; ow.x = cvtpk(a * c0[0] - b * c0[1], a * c0[1] + b * c0[0]); }
;             { const float a = bflo(w.y) * cs, b = bfhi(w.y) * cs; ow.y = cvtpk(a * c0[2] - b * c0[3], a * c0[3] + b * c0[2]); }
;             { const float a = bflo(w.z) * cs, b = bfhi(w.z) * cs; ow.z = cvtpk(a * c1[0] - b * c1[1], a * c1[1] + b * c1[0]); }
;             { const float a = bflo(w.w) * cs, b = bfhi(w.w) * cs; ow.w = cvtpk(a * c1[2] - b * c1[3], a * c1[3] + b * c1[2]); }
;             qf[ks] = __builtin_bit_cast(bf16x8, ow);
;         }
;     }
; #pragma unroll
;     for (int d = 0; d < NDT; ++d)
; #pragma unroll
;         for (int r = 0; r < 16; ++r) o[d][r] = 0.f;
; #pragma unroll
;     for (int ks = 0; ks < NKS; ++ks) asm volatile("" : "+v"(qf[ks]));
;     float mhat = 0.f, l = 0.f; f32x16 negm;
; #pragma unroll
;     for (int r = 0; r < 16; ++r) negm[r] = 0.f;
;     constexpr int TPB = (DV == 64) ? 2 : 1, NG = SEQL / 64 / TPB;
;     u32x4 kreg[TPB], k2reg[TPB], vreg[TPB][NVL];
;     const bf16_t* kptr = Kg + (size_t)(tid >> 3) * ldk + (tid & 7) * 8;
;     const bf16_t* k2ptr = (DQK == 96) ? K2g + (size_t)(tid >> 2) * ldk2 + (tid & 3) * 8 : nullptr;
;     ...
;     u32x4 pw[4];
; #pragma unroll
;     for (int j = 0; j < TPB; ++j) { ATT_LOAD(j, j); ATT_STORE(j, j); }
; #pragma unroll
;     for (int j = 0; j < TPB; ++j) ATT_LOAD(TPB + j, j);
;     const float qp = (float)(qpos0 + r32);
	v_lshlrev_b32_e32 v18, 16, v2
	v_and_b32_e32 v19, 0xffff0000, v2
	v_lshlrev_b32_e32 v2, 16, v3
	v_and_b32_e32 v3, 0xffff0000, v3
	v_lshlrev_b32_e32 v30, 16, v14
	v_pk_mul_f32 v[2:3], v[2:3], s[6:7] op_sel_hi:[1,0]
	v_and_b32_e32 v31, 0xffff0000, v14
	v_cvt_pk_bf16_f32 v115, v2, v3
	v_pk_mul_f32 v[2:3], v[30:31], s[6:7] op_sel_hi:[1,0]
	v_lshlrev_b32_e32 v22, 16, v6
	v_cvt_pk_bf16_f32 v126, v2, v3
	v_lshlrev_b32_e32 v2, 16, v15
	v_and_b32_e32 v3, 0xffff0000, v15
	v_pk_mul_f32 v[2:3], v[2:3], s[6:7] op_sel_hi:[1,0]
	v_and_b32_e32 v23, 0xffff0000, v6
	v_cvt_pk_bf16_f32 v127, v2, v3
	v_lshlrev_b32_e32 v2, 16, v16
	v_and_b32_e32 v3, 0xffff0000, v16
	v_pk_mul_f32 v[2:3], v[2:3], s[6:7] op_sel_hi:[1,0]
	v_lshlrev_b32_e32 v24, 16, v8
	v_cvt_pk_bf16_f32 v128, v2, v3
	v_lshlrev_b32_e32 v2, 16, v17
	v_and_b32_e32 v3, 0xffff0000, v17
	v_and_b32_e32 v25, 0xffff0000, v8
	v_pk_mul_f32 v[22:23], v[22:23], s[6:7] op_sel_hi:[1,0]
	v_pk_mul_f32 v[2:3], v[2:3], s[6:7] op_sel_hi:[1,0]
	v_lshlrev_b32_e32 v20, 16, v4
	v_and_b32_e32 v21, 0xffff0000, v4
	v_lshlrev_b32_e32 v4, 16, v5
	v_and_b32_e32 v5, 0xffff0000, v5
	v_pk_mul_f32 v[24:25], v[24:25], s[6:7] op_sel_hi:[1,0]
	v_cvt_pk_bf16_f32 v118, v22, v23
	v_cvt_pk_bf16_f32 v129, v2, v3
	v_ashrrev_i32_e32 v22, 3, v32
	v_mov_b64_e32 v[2:3], s[4:5]
	v_lshlrev_b32_e32 v23, 4, v32
	v_pk_mul_f32 v[4:5], v[4:5], s[6:7] op_sel_hi:[1,0]
	v_cvt_pk_bf16_f32 v120, v24, v25
	v_mad_i64_i32 v[2:3], s[10:11], v22, s7, v[2:3]
	v_and_b32_e32 v14, 0x70, v23
	v_mov_b32_e32 v15, v151
	v_bfe_u32 v24, v32, 2, 6
	v_cvt_pk_bf16_f32 v117, v4, v5
	v_lshl_add_u64 v[144:145], v[2:3], 0, v[14:15]
	v_subrev_u32_e32 v232, s4, v144
	s_sub_u32 s98, s4, s16
	s_subb_u32 s99, s5, s17
	v_mul_u32_u24_e32 v2, 0xca0, v24
	v_lshlrev_b32_e32 v4, 3, v32
	v_lshlrev_b32_e32 v2, 1, v2
	v_mov_b32_e32 v3, v151
	v_and_b32_e32 v25, 24, v4
	v_lshl_add_u64 v[2:3], s[4:5], 0, v[2:3]
	v_lshlrev_b32_e32 v4, 1, v25
	v_mov_b32_e32 v5, v151
	v_lshl_add_u64 v[16:17], v[2:3], 0, v[4:5]
	v_and_b32_e32 v2, 0xffffffe0, v22
	v_lshlrev_b32_e32 v6, 16, v7
	v_and_b32_e32 v7, 0xffff0000, v7
	v_lshlrev_b32_e32 v8, 16, v9
	v_and_b32_e32 v9, 0xffff0000, v9
	v_lshlrev_b32_e32 v26, 16, v10
	v_and_b32_e32 v27, 0xffff0000, v10
	v_lshlrev_b32_e32 v10, 16, v11
	v_and_b32_e32 v11, 0xffff0000, v11
	v_lshlrev_b32_e32 v28, 16, v12
	v_and_b32_e32 v29, 0xffff0000, v12
	v_lshlrev_b32_e32 v12, 16, v13
	v_and_b32_e32 v13, 0xffff0000, v13
	v_pk_mul_f32 v[18:19], v[18:19], s[6:7] op_sel_hi:[1,0]
	v_ashrrev_i32_e32 v3, 31, v2
	v_pk_mul_f32 v[20:21], v[20:21], s[6:7] op_sel_hi:[1,0]
	v_pk_mul_f32 v[6:7], v[6:7], s[6:7] op_sel_hi:[1,0]
	v_pk_mul_f32 v[8:9], v[8:9], s[6:7] op_sel_hi:[1,0]
	v_pk_mul_f32 v[26:27], v[26:27], s[6:7] op_sel_hi:[1,0]
	v_pk_mul_f32 v[10:11], v[10:11], s[6:7] op_sel_hi:[1,0]
	v_pk_mul_f32 v[28:29], v[28:29], s[6:7] op_sel_hi:[1,0]
	v_pk_mul_f32 v[12:13], v[12:13], s[6:7] op_sel_hi:[1,0]
	v_cvt_pk_bf16_f32 v114, v18, v19
	v_lshlrev_b64 v[18:19], 1, v[2:3]
	v_cvt_pk_bf16_f32 v116, v20, v21
	v_cvt_pk_bf16_f32 v119, v6, v7
	v_cvt_pk_bf16_f32 v121, v8, v9
	v_cvt_pk_bf16_f32 v122, v26, v27
	v_cvt_pk_bf16_f32 v123, v10, v11
	v_cvt_pk_bf16_f32 v124, v28, v29
	v_cvt_pk_bf16_f32 v125, v12, v13
	v_lshl_add_u64 v[10:11], v[16:17], 0, v[18:19]
	global_load_dwordx4 v[2:5], v[144:145], off offset:1024
	global_load_dwordx4 v[6:9], v[10:11], off offset:2048
	v_add_u32_e32 v10, 0x200, v32
	v_ashrrev_i32_e32 v10, 3, v10
	v_and_b32_e32 v10, 0xffffffe0, v10
	v_ashrrev_i32_e32 v11, 31, v10
	v_lshlrev_b64 v[20:21], 1, v[10:11]
	v_lshl_add_u64 v[10:11], v[16:17], 0, v[20:21]
	global_load_dwordx4 v[10:13], v[10:11], off offset:2048
	s_movk_i32 s6, 0x90
	v_mul_lo_u32 v15, v22, s6
	s_mov_b64 s[10:11], 0x65800
	v_and_b32_e32 v22, 0xfc0, v23
	v_and_b32_e32 v27, 48, v23
	v_add_u32_e32 v15, 0, v15
	v_and_b32_e32 v23, 0xfffff000, v23
	v_add3_u32 v22, 0, v22, v27
	v_add_u32_e32 v168, v15, v14
	v_lshl_add_u64 v[14:15], v[16:17], 0, s[10:11]
	v_add_u32_e32 v171, v22, v23
	v_lshl_add_u64 v[16:17], v[14:15], 0, v[18:19]
	v_add_co_u32_e32 v22, vcc, s8, v144
	v_lshl_add_u64 v[14:15], v[14:15], 0, v[20:21]
	s_nop 0
	v_addc_co_u32_e32 v23, vcc, 0, v145, vcc
	global_load_dwordx4 v[130:133], v[16:17], off
	global_load_dwordx4 v[134:137], v[14:15], off
	global_load_dwordx4 v[138:141], v[22:23], off offset:1024
	v_cvt_f32_i32_e32 v28, s3
	s_add_i32 s3, s46, s27
	v_lshrrev_b32_e32 v26, 2, v32
	s_waitcnt vmcnt(5)
	ds_write_b128 v168, v[2:5]
	s_waitcnt vmcnt(4)
	ds_write_b128 v171, v[6:9] offset:18432
	s_waitcnt vmcnt(3)
	ds_write_b128 v171, v[10:13] offset:26624
	v_or_b32_e32 v2, s3, v33
	v_cvt_f32_i32_e32 v172, v2
	v_and_or_b32 v2, v26, 3, v173
	v_lshlrev_b32_e32 v3, 1, v32
	v_mad_u32_u24 v22, v33, s6, 0
	v_lshl_add_u32 v2, v2, 6, 0
	v_and_b32_e32 v3, 32, v3
	s_or_b32 s6, s49, s9
	v_exp_f32_e32 v27, v28
	v_add3_u32 v174, v2, v3, v25
	v_mov_b32_e32 v2, s6
	v_mov_b32_e32 v3, s48
	v_mad_u64_u32 v[2:3], s[6:7], v24, s7, v[2:3]
	v_and_b32_e32 v4, 3, v32
	v_lshl_or_b32 v2, v4, 4, v2
	v_lshl_add_u64 v[4:5], v[2:3], 0, v[20:21]
	v_lshl_add_u64 v[2:3], v[2:3], 0, v[18:19]
	v_mov_b32_e32 v16, v151
	v_mov_b32_e32 v17, v151
	v_mbcnt_lo_u32_b32 v18, -1, 0
	v_mul_f32_e32 v142, 0x3fb8aa3b, v27
	v_mov_b32_e32 v231, v4
	v_lshl_add_u64 v[146:147], s[16:17], 0, v[4:5]
	v_mov_b32_e32 v230, v2
	v_lshl_add_u64 v[148:149], s[16:17], 0, v[2:3]
	v_mov_b32_e32 v2, v151
	v_mov_b32_e32 v3, v151
	v_mov_b32_e32 v4, v151
	v_mov_b32_e32 v5, v151
	v_mov_b32_e32 v6, v151
	v_mov_b32_e32 v7, v151
	v_mov_b32_e32 v8, v151
	v_mov_b32_e32 v9, v151
	v_mov_b32_e32 v10, v151
	v_mov_b32_e32 v11, v151
	v_mov_b32_e32 v12, v151
	v_mov_b32_e32 v13, v151
	v_mov_b32_e32 v14, v151
	v_mov_b32_e32 v15, v151
	s_mov_b32 s10, -2.0
	v_add_u32_e32 v175, v22, v150
	v_mbcnt_hi_u32_b32 v170, -1, v18
	v_mov_b64_e32 v[32:33], v[16:17]
	v_mov_b64_e32 v[48:49], v[16:17]
	v_mov_b64_e32 v[64:65], v[16:17]
	v_mov_b32_e32 v143, v142
	s_mov_b64 s[6:7], 0
	s_mov_b32 s8, 0xc2000000
	s_mov_b32 s11, 0xc0400000
	v_mov_b64_e32 v[30:31], v[14:15]
	v_mov_b64_e32 v[28:29], v[12:13]
	v_mov_b64_e32 v[26:27], v[10:11]
	v_mov_b64_e32 v[24:25], v[8:9]
	v_mov_b64_e32 v[22:23], v[6:7]
	v_mov_b64_e32 v[20:21], v[4:5]
	v_mov_b64_e32 v[18:19], v[2:3]
	v_mov_b64_e32 v[46:47], v[14:15]
	v_mov_b64_e32 v[44:45], v[12:13]
	v_mov_b64_e32 v[42:43], v[10:11]
	v_mov_b64_e32 v[40:41], v[8:9]
	v_mov_b64_e32 v[38:39], v[6:7]
	v_mov_b64_e32 v[36:37], v[4:5]
	v_mov_b64_e32 v[34:35], v[2:3]
	v_mov_b64_e32 v[62:63], v[14:15]
	v_mov_b64_e32 v[60:61], v[12:13]
	v_mov_b64_e32 v[58:59], v[10:11]
	v_mov_b64_e32 v[56:57], v[8:9]
	v_mov_b64_e32 v[54:55], v[6:7]
	v_mov_b64_e32 v[52:53], v[4:5]
	v_mov_b64_e32 v[50:51], v[2:3]
	s_branch .LBB0_2004

; __global__ void __launch_bounds__(512, 2) fwd_mega(Params Pv) {
	.amdhsa_kernel _Z8fwd_mega6Params
		.amdhsa_group_segment_fixed_size 0
		.amdhsa_private_segment_fixed_size 0
		.amdhsa_kernarg_size 552
		.amdhsa_user_sgpr_count 2
		.amdhsa_user_sgpr_dispatch_ptr 0
		.amdhsa_user_sgpr_queue_ptr 0
		.amdhsa_user_sgpr_kernarg_segment_ptr 1
		.amdhsa_user_sgpr_dispatch_id 0
		.amdhsa_user_sgpr_kernarg_preload_length 0
		.amdhsa_user_sgpr_kernarg_preload_offset 0
		.amdhsa_user_sgpr_private_segment_size 0
		.amdhsa_uses_dynamic_stack 0
		.amdhsa_enable_private_segment 0
		.amdhsa_system_sgpr_workgroup_id_x 1
		.amdhsa_system_sgpr_workgroup_id_y 0
		.amdhsa_system_sgpr_workgroup_id_z 0
		.amdhsa_system_sgpr_workgroup_info 0
		.amdhsa_system_vgpr_workitem_id 2
		.amdhsa_next_free_vgpr 240
		.amdhsa_next_free_sgpr 102
		.amdhsa_accum_offset 240
		.amdhsa_reserve_vcc 1
		.amdhsa_float_round_mode_32 0
		.amdhsa_float_round_mode_16_64 0
		.amdhsa_float_denorm_mode_32 3
		.amdhsa_float_denorm_mode_16_64 3
		.amdhsa_dx10_clamp 1
		.amdhsa_ieee_mode 1
		.amdhsa_fp16_overflow 0
		.amdhsa_tg_split 0
		.amdhsa_exception_fp_ieee_invalid_op 0
		.amdhsa_exception_fp_denorm_src 0
		.amdhsa_exception_fp_ieee_div_zero 0
		.amdhsa_exception_fp_ieee_overflow 0
		.amdhsa_exception_fp_ieee_underflow 0
		.amdhsa_exception_fp_ieee_inexact 0
		.amdhsa_exception_int_div_zero 0
	.end_amdhsa_kernel

; #define LAS __attribute__((address_space(3)))
; #define PHASE(n) if (ph_lo <= (n) && (n) < ph_hi) { phase_body<n>(lds, vcu, NGW); if ((n) + 1 < ph_hi) { if (ph_hi > NPHASE) { __syncthreads(); cg::this_grid().sync(); } else xcd_barrier(xbar); } }
; __global__ void __launch_bounds__(512, 2) fwd_mega(Params Pv) {
;     extern __shared__ __attribute__((aligned(16))) unsigned char lds_raw[];
;     LAS unsigned char* lds = (LAS unsigned char*)lds_raw;
;     const int G = gridDim.x, bx = blockIdx.x; const int vcu = (G % 8 == 0) ? (bx % 8) * (G / 8) + bx / 8 : bx; const int NGW = G * 8;
;     const int ph_lo = Pv.ph_lo, ph_hi = Pv.ph_hi;
;     volatile LAS unsigned* bst = (volatile LAS unsigned*)(lds + 147456);
;     if (threadIdx.x < 2) bst[threadIdx.x] = 0u;
;     __syncthreads();
;     XcdBarrier xbar = xcd_barrier_post((unsigned*)(Pv.ws + OFF_CTL), bst);
;     ...
;     PHASE(0) PHASE(1) PHASE(2) PHASE(3) PHASE(4) PHASE(5) PHASE(6) PHASE(7) PHASE(8) PHASE(9) PHASE(10)
;     PHASE(11) PHASE(12) PHASE(13) PHASE(14) PHASE(15) PHASE(16) PHASE(17) PHASE(18) PHASE(19) PHASE(20)
;     ...
; }
amdhsa.kernels:
  - .agpr_count:     0
    .args:
      - .offset:         0
        .size:           296
        .value_kind:     by_value
      - .offset:         296
        .size:           4
        .value_kind:     hidden_block_count_x
      - .offset:         300
        .size:           4
        .value_kind:     hidden_block_count_y
      - .offset:         304
        .size:           4
        .value_kind:     hidden_block_count_z
      - .offset:         308
        .size:           2
        .value_kind:     hidden_group_size_x
      - .offset:         310
        .size:           2
        .value_kind:     hidden_group_size_y
      - .offset:         312
        .size:           2
        .value_kind:     hidden_group_size_z
      - .offset:         314
        .size:           2
        .value_kind:     hidden_remainder_x
      - .offset:         316
        .size:           2
        .value_kind:     hidden_remainder_y
      - .offset:         318
        .size:           2
        .value_kind:     hidden_remainder_z
      - .offset:         336
        .size:           8
        .value_kind:     hidden_global_offset_x
      - .offset:         344
        .size:           8
        .value_kind:     hidden_global_offset_y
      - .offset:         352
        .size:           8
        .value_kind:     hidden_global_offset_z
      - .offset:         360
        .size:           2
        .value_kind:     hidden_grid_dims
      - .offset:         384
        .size:           8
        .value_kind:     hidden_multigrid_sync_arg
      - .offset:         416
        .size:           4
        .value_kind:     hidden_dynamic_lds_size
    .group_segment_fixed_size: 0
    .kernarg_segment_align: 8
    .kernarg_segment_size: 552
    .language:       OpenCL C
    .language_version:
      - 2
      - 0
    .max_flat_workgroup_size: 512
    .name:           _Z8fwd_mega6Params
    .private_segment_fixed_size: 0
    .sgpr_count:     108
    .sgpr_spill_count: 0
    .symbol:         _Z8fwd_mega6Params.kd
    .uniform_work_group_size: 1
    .uses_dynamic_stack: false
    .vgpr_count:     240
    .vgpr_spill_count: 0
    .wavefront_size: 64
